# attention K-loop: LDS-DMA pieces issued one per QK step (saddr form, scalar running pointers) instead of a burst after the barrier; 2-deep K fragment reads; 4-slot V ring with counted vmcnt(2); epilog
# speedup vs baseline: 1.0251x; 1.0188x over previous
; #define LANE_ID() (__builtin_amdgcn_mbcnt_hi(~0u, __builtin_amdgcn_mbcnt_lo(~0u, 0u)))
; #define WSL() const CAS Params* pp = (const CAS Params*)__builtin_amdgcn_kernarg_segment_ptr(); asm volatile("" : "+s"(pp)); unsigned char* wsl = pp->ws; asm volatile("" : "+s"(wsl))
; __global__ void __launch_bounds__(NTHREADS, 2) mega(Params P) {
;     ...
;             WSL(); int lane = LANE_ID(); asm volatile("" : "+v"(lane)); const bf16_t* WPt = (const bf16_t*)(wsl + WS_WP + l * SZ_WP);
;             const int nunits = 1024 + (l < DEPTH - 1 ? 16 : 0);
;             float kmax; { const float* kn = pp->k_norm + l * 128; kmax = fmaxf(fabsf(kn[lane]), fabsf(kn[lane + 64]));
; #pragma unroll
;                 for (int o_ = 1; o_ < 64; o_ <<= 1) kmax = fmaxf(kmax, __shfl_xor(kmax, o_)); }
;             for (int un = bid; un < nunits; un += G) {
.LBB0_109:
	v_mov_b64_e32 v[242:243], 0xb2b
	s_andn2_b64 vcc, exec, s[0:1]
	s_cbranch_vccnz .LBB0_147
	v_readlane_b32 s0, v253, 0
	v_readlane_b32 s1, v253, 1
	s_waitcnt lgkmcnt(0)
	s_load_dwordx2 s[42:43], s[0:1], 0x88
	v_mov_b32_e32 v144, v236
	s_waitcnt lgkmcnt(0)
	s_load_dwordx2 s[8:9], s[0:1], 0x40
	s_lshl_b32 s7, s67, 9
	v_ashrrev_i32_e32 v145, 31, v144
	s_movk_i32 s6, 0x410
	s_waitcnt lgkmcnt(0)
	s_add_u32 s8, s8, s7
	s_addc_u32 s9, s9, 0
	v_lshl_add_u64 v[0:1], v[144:145], 2, s[8:9]
	global_load_dword v2, v[0:1], off offset:256
	s_nop 0
	global_load_dword v0, v[0:1], off
	v_xor_b32_e32 v1, 1, v236
	v_cmp_lt_i32_e32 vcc, v1, v237
	s_cmp_lt_u32 s67, 3
	s_cselect_b64 s[38:39], -1, 0
	v_cndmask_b32_e32 v1, v236, v1, vcc
	v_lshlrev_b32_e32 v1, 2, v1
	s_and_b64 s[8:9], s[38:39], exec
	s_cselect_b32 s6, s6, 0x400
	s_cmp_ge_i32 s2, s6
	s_waitcnt vmcnt(0)
	v_max_f32_e64 v2, |v2|, |v2|
	v_max_f32_e64 v0, |v0|, |v0|
	v_max_f32_e32 v0, v0, v2
	ds_bpermute_b32 v1, v1, v0
	v_xor_b32_e32 v2, 2, v236
	v_cmp_lt_i32_e32 vcc, v2, v237
	s_waitcnt lgkmcnt(0)
	v_max_f32_e32 v1, v1, v1
	v_cndmask_b32_e32 v2, v236, v2, vcc
	v_lshlrev_b32_e32 v2, 2, v2
	v_max_f32_e32 v0, v0, v1
	ds_bpermute_b32 v1, v2, v0
	v_xor_b32_e32 v2, 4, v236
	v_cmp_lt_i32_e32 vcc, v2, v237
	s_waitcnt lgkmcnt(0)
	v_max_f32_e32 v1, v1, v1
	v_cndmask_b32_e32 v2, v236, v2, vcc
	v_lshlrev_b32_e32 v2, 2, v2
	v_max_f32_e32 v0, v0, v1
	ds_bpermute_b32 v1, v2, v0
	v_xor_b32_e32 v2, 8, v236
	v_cmp_lt_i32_e32 vcc, v2, v237
	s_waitcnt lgkmcnt(0)
	v_max_f32_e32 v1, v1, v1
	v_cndmask_b32_e32 v2, v236, v2, vcc
	v_lshlrev_b32_e32 v2, 2, v2
	v_max_f32_e32 v0, v0, v1
	ds_bpermute_b32 v1, v2, v0
	v_cmp_lt_i32_e32 vcc, v252, v237
	s_waitcnt lgkmcnt(0)
	v_max_f32_e32 v1, v1, v1
	v_cndmask_b32_e32 v2, v236, v252, vcc
	v_lshlrev_b32_e32 v2, 2, v2
	v_max_f32_e32 v0, v0, v1
	ds_bpermute_b32 v1, v2, v0
	v_xor_b32_e32 v2, 32, v236
	v_cmp_lt_i32_e32 vcc, v2, v237
	s_waitcnt lgkmcnt(0)
	v_max_f32_e32 v1, v1, v1
	v_cndmask_b32_e32 v2, v236, v2, vcc
	v_max_f32_e32 v0, v0, v1
	v_lshlrev_b32_e32 v1, 2, v2
	ds_bpermute_b32 v1, v1, v0
	s_cbranch_scc1 .LBB0_119
	v_writelane_b32 v255, s84, 16
	v_writelane_b32 v255, s85, 17
	v_writelane_b32 v255, s86, 18
	v_writelane_b32 v255, s87, 19
	s_add_u32 s8, s42, 0x83b4000
	s_addc_u32 s9, s43, 0
	s_add_u32 s10, s42, 0xc4b4000
	s_addc_u32 s11, s43, 0
	s_add_u32 s12, s42, 0xd4f4000
	s_addc_u32 s13, s43, 0
	s_waitcnt lgkmcnt(0)
	v_max_f32_e32 v1, v1, v1
	v_max_f32_e32 v0, v0, v0
	s_add_u32 s36, s42, 0xe534000
	v_max_f32_e32 v145, v0, v1
	s_addc_u32 s50, s43, 0
	s_mov_b32 s51, s2

; __device__ __forceinline__ void attn_dense_body(const bf16* Qb, const bf16* __restrict__ Kh, const bf16* __restrict__ Vh, const bf16* __restrict__ Zb, ...
;     ...
;   const TQ* Qw = Qb + (long)(wid * QBLK + r32) * LDQ + hi * 8;
; #pragma unroll
;   for (int d0 = 0; d0 < 8; ++d0) qr[d0] = SQ::tobf(SQ::ld8(Qw + d0 * 16));
;   float negBC;
;   { float ss = 0.f;
; #pragma unroll
;     for (int d0 = 0; d0 < 8; ++d0)
; #pragma unroll
;       for (int e = 0; e < 8; ++e) { const float qv = __uint_as_float((unsigned)(unsigned short)qr[d0][e] << 16); ss = fmaf(qv, qv, ss); }
;     auto rr = __builtin_amdgcn_permlane32_swap(__float_as_uint(ss), __float_as_uint(ss), false, false);
;     ss = __uint_as_float(rr[0]) + __uint_as_float(rr[1]);
; __global__ void __launch_bounds__(NTHREADS, 2) mega(Params P) {
;     ...
;                 __syncthreads();
;                 int b, h, rowq, seq;
;                 if (un < 1024) { b = un >> 9; h = (un >> 6) & 7; rowq = b * TB + CTXL + (un & 63) * 256; seq = TB; }
;                 else { const int c = un - 1024; b = c >> 3; h = c & 7; rowq = b * TB; seq = CTXL; }
;                 const size_t qoff = (size_t)rowq * DM + h * 128, koff = (size_t)b * TB * 256 + (h >> 2) * 128;
.LBB0_116:
	s_and_b32 s16, s15, 7
	s_ashr_i32 s25, s24, 31
	s_lshl_b64 s[24:25], s[24:25], 10
	s_lshl_b32 s16, s16, 7
	s_lshl_b32 s17, s15, 5
	s_or_b32 s24, s24, s16
	s_mul_i32 s16, s14, 0x410000
	s_and_b32 s17, s17, 0x80
	v_mov_b32_e32 v32, v236
	s_or_b32 s40, s16, s17
	s_lshl_b64 s[44:45], s[24:25], 1
	s_add_u32 s24, s8, s44
	v_and_b32_e32 v10, 31, v32
	v_ashrrev_i32_e32 v245, 5, v32
	v_or_b32_e32 v160, s69, v10
	s_addc_u32 s25, s9, s45
	v_lshlrev_b64 v[0:1], 11, v[160:161]
	v_lshlrev_b32_e32 v2, 3, v245
	v_lshl_add_u64 v[0:1], s[24:25], 0, v[0:1]
	v_ashrrev_i32_e32 v3, 31, v2
	v_lshl_add_u64 v[0:1], v[2:3], 1, v[0:1]
	flat_load_dwordx4 v[140:143], v[0:1]
	flat_load_dwordx4 v[136:139], v[0:1] offset:32
	flat_load_dwordx4 v[132:135], v[0:1] offset:64
	flat_load_dwordx4 v[128:131], v[0:1] offset:96
	flat_load_dwordx4 v[124:127], v[0:1] offset:128
	flat_load_dwordx4 v[120:123], v[0:1] offset:160
	flat_load_dwordx4 v[116:119], v[0:1] offset:192
	flat_load_dwordx4 v[112:115], v[0:1] offset:224
	s_mov_b32 s16, 0xf800000
	s_mul_hi_i32 s41, s14, 0x410000
	s_lshl_b64 s[40:41], s[40:41], 1
	s_add_u32 s46, s10, s40
	s_addc_u32 s47, s11, s41
	s_add_u32 s48, s12, s40
	s_addc_u32 s49, s13, s41
	s_add_i32 m0, s90, 0xc000
	v_mov_b32_e32 v146, 0
	s_mov_b32 s54, 0
	v_mov_b32_e32 v58, v146
	v_mov_b32_e32 v59, v146
	v_mov_b32_e32 v60, v146
	v_mov_b32_e32 v61, v146
	v_mov_b32_e32 v62, v146
	v_mov_b32_e32 v63, v146
	s_waitcnt vmcnt(0) lgkmcnt(0)
	v_lshlrev_b32_e32 v0, 16, v140
	v_and_b32_e32 v1, 0xffff0000, v140
	v_fma_f32 v0, v0, v0, 0
	v_lshlrev_b32_e32 v2, 16, v141
	v_fmac_f32_e32 v0, v1, v1
	v_and_b32_e32 v3, 0xffff0000, v141
	v_fmac_f32_e32 v0, v2, v2
	v_lshlrev_b32_e32 v4, 16, v142
	v_fmac_f32_e32 v0, v3, v3
	v_and_b32_e32 v5, 0xffff0000, v142
	v_fmac_f32_e32 v0, v4, v4
	v_lshlrev_b32_e32 v6, 16, v143
	v_fmac_f32_e32 v0, v5, v5
	v_and_b32_e32 v7, 0xffff0000, v143
	v_fmac_f32_e32 v0, v6, v6
	v_lshlrev_b32_e32 v8, 16, v136
	v_fmac_f32_e32 v0, v7, v7
	v_and_b32_e32 v9, 0xffff0000, v136
	v_fmac_f32_e32 v0, v8, v8
	v_lshlrev_b32_e32 v11, 16, v137
	v_fmac_f32_e32 v0, v9, v9
	v_and_b32_e32 v12, 0xffff0000, v137
	v_fmac_f32_e32 v0, v11, v11
	v_lshlrev_b32_e32 v13, 16, v138
	v_fmac_f32_e32 v0, v12, v12
	v_and_b32_e32 v14, 0xffff0000, v138
	v_fmac_f32_e32 v0, v13, v13
	v_lshlrev_b32_e32 v15, 16, v139
	v_fmac_f32_e32 v0, v14, v14
	v_and_b32_e32 v16, 0xffff0000, v139
	v_fmac_f32_e32 v0, v15, v15
	v_lshlrev_b32_e32 v17, 16, v132
	v_fmac_f32_e32 v0, v16, v16
	v_and_b32_e32 v18, 0xffff0000, v132
	v_fmac_f32_e32 v0, v17, v17
	v_lshlrev_b32_e32 v19, 16, v133
	v_fmac_f32_e32 v0, v18, v18
	v_and_b32_e32 v20, 0xffff0000, v133
	v_fmac_f32_e32 v0, v19, v19
	v_lshlrev_b32_e32 v21, 16, v134
	v_fmac_f32_e32 v0, v20, v20
	v_and_b32_e32 v22, 0xffff0000, v134
	v_fmac_f32_e32 v0, v21, v21
	v_lshlrev_b32_e32 v23, 16, v135
	v_fmac_f32_e32 v0, v22, v22
	v_and_b32_e32 v24, 0xffff0000, v135
	v_fmac_f32_e32 v0, v23, v23
	v_lshlrev_b32_e32 v25, 16, v128
	v_fmac_f32_e32 v0, v24, v24
	v_and_b32_e32 v26, 0xffff0000, v128
	v_fmac_f32_e32 v0, v25, v25
	v_lshlrev_b32_e32 v27, 16, v129
	v_fmac_f32_e32 v0, v26, v26
	v_and_b32_e32 v28, 0xffff0000, v129
	v_fmac_f32_e32 v0, v27, v27
	v_lshlrev_b32_e32 v29, 16, v130
	v_fmac_f32_e32 v0, v28, v28
	v_and_b32_e32 v30, 0xffff0000, v130
	v_fmac_f32_e32 v0, v29, v29
	v_lshlrev_b32_e32 v31, 16, v131
	v_fmac_f32_e32 v0, v30, v30
	v_and_b32_e32 v33, 0xffff0000, v131
	v_fmac_f32_e32 v0, v31, v31
	v_lshlrev_b32_e32 v34, 16, v124
	v_fmac_f32_e32 v0, v33, v33
	v_and_b32_e32 v35, 0xffff0000, v124
	v_fmac_f32_e32 v0, v34, v34
	v_lshlrev_b32_e32 v36, 16, v125
	v_fmac_f32_e32 v0, v35, v35
	v_and_b32_e32 v37, 0xffff0000, v125
	v_fmac_f32_e32 v0, v36, v36
	v_lshlrev_b32_e32 v38, 16, v126
	v_fmac_f32_e32 v0, v37, v37
	v_and_b32_e32 v39, 0xffff0000, v126
	v_fmac_f32_e32 v0, v38, v38
	v_lshlrev_b32_e32 v40, 16, v127
	v_fmac_f32_e32 v0, v39, v39
	v_and_b32_e32 v41, 0xffff0000, v127
	v_fmac_f32_e32 v0, v40, v40
	v_lshlrev_b32_e32 v42, 16, v120
	v_fmac_f32_e32 v0, v41, v41
	v_and_b32_e32 v43, 0xffff0000, v120
	v_fmac_f32_e32 v0, v42, v42
	v_lshlrev_b32_e32 v44, 16, v121
	v_fmac_f32_e32 v0, v43, v43
	v_and_b32_e32 v45, 0xffff0000, v121
	v_fmac_f32_e32 v0, v44, v44
	v_lshlrev_b32_e32 v46, 16, v122
	v_fmac_f32_e32 v0, v45, v45
	v_and_b32_e32 v47, 0xffff0000, v122
	v_fmac_f32_e32 v0, v46, v46
	v_lshlrev_b32_e32 v48, 16, v123
	v_fmac_f32_e32 v0, v47, v47
	v_and_b32_e32 v49, 0xffff0000, v123
	v_fmac_f32_e32 v0, v48, v48
	v_lshlrev_b32_e32 v50, 16, v116
	v_fmac_f32_e32 v0, v49, v49
	v_and_b32_e32 v51, 0xffff0000, v116
	v_fmac_f32_e32 v0, v50, v50
	v_lshlrev_b32_e32 v52, 16, v117
	v_fmac_f32_e32 v0, v51, v51
	v_and_b32_e32 v53, 0xffff0000, v117
	v_fmac_f32_e32 v0, v52, v52
	v_lshlrev_b32_e32 v54, 16, v118
	v_fmac_f32_e32 v0, v53, v53
	v_and_b32_e32 v55, 0xffff0000, v118
	v_fmac_f32_e32 v0, v54, v54
	v_lshlrev_b32_e32 v56, 16, v119
	v_fmac_f32_e32 v0, v55, v55
	v_and_b32_e32 v57, 0xffff0000, v119
	v_fmac_f32_e32 v0, v56, v56
	v_fmac_f32_e32 v0, v57, v57
	v_lshlrev_b32_e32 v1, 16, v112
	v_fmac_f32_e32 v0, v1, v1
	v_and_b32_e32 v1, 0xffff0000, v112
	v_fmac_f32_e32 v0, v1, v1
	v_lshlrev_b32_e32 v1, 16, v113
	v_fmac_f32_e32 v0, v1, v1
	v_and_b32_e32 v1, 0xffff0000, v113
	v_fmac_f32_e32 v0, v1, v1
	v_lshlrev_b32_e32 v1, 16, v114
	v_fmac_f32_e32 v0, v1, v1
	v_and_b32_e32 v1, 0xffff0000, v114
	v_fmac_f32_e32 v0, v1, v1
	v_lshlrev_b32_e32 v1, 16, v115
	v_fmac_f32_e32 v0, v1, v1
	v_and_b32_e32 v1, 0xffff0000, v115
	v_fmac_f32_e32 v0, v1, v1
	v_mov_b32_e32 v1, v0
	s_nop 1
	v_permlane32_swap_b32_e32 v0, v1
	v_add_f32_e32 v0, v0, v1
	v_mul_f32_e32 v1, 0x4f800000, v0
	v_cmp_gt_f32_e32 vcc, s16, v0
; __device__ __forceinline__ void partialSM3(f32x16& p0) { for (int r = 0; r < 16; ++r) p0[r] = __builtin_amdgcn_exp2f(p0[r]); }
; __device__ __forceinline__ int v_rd_base2(int lane) { return ((lane & 3) << 3) | (((lane >> 2) & 3) << 6) | (((lane >> 4) & 1) << 5) | (((lane >> 5) & 1) << 11); }
; #define DWAIT() asm volatile("s_waitcnt vmcnt(0)" ::: "memory")
; __device__ __forceinline__ void attn_dense_body(const bf16* Qb, const bf16* __restrict__ Kh, const bf16* __restrict__ Vh, const bf16* __restrict__ Zb, ...
;     ...
;     negBC = -(sqrtf(ss) * kmax * (11.313708498984761f * 1.01f) + 0.07f); }
;   f32x16 cinit; for (int r = 0; r < 16; ++r) cinit[r] = negBC;
;   const int vb0 = (int)(uintptr_t)V_lds + v_rd_base2(lane);
;   int koff0, koff1, voff0, voff1;
;   { const int rk0 = 8 * wid + (lane >> 4), rk1 = rk0 + 4; koff0 = rk0 * (LDK * 2) + (((lane & 15) ^ (rk0 & 15)) << 4); koff1 = rk1 * (LDK * 2) + (((lane & 15) ^ (rk1 & 15)) << 4);
;     const int st0 = 4 * wid + (lane >> 5), st1 = st0 + 2, q8 = (lane & 31) >> 2;
;     const int kk0 = ((st0 >> 2) << 3) | q8, kk1 = ((st1 >> 2) << 3) | q8;
;     const int ky0 = (kk0 & ~0xC) | ((kk0 & 4) << 1) | ((kk0 & 8) >> 1), ky1 = (kk1 & ~0xC) | ((kk1 & 4) << 1) | ((kk1 & 8) >> 1);
;     voff0 = ky0 * (LDK * 2) + ((st0 & 3) * 32 + (lane & 3) * 8) * 2; voff1 = ky1 * (LDK * 2) + ((st1 & 3) * 32 + (lane & 3) * 8) * 2; }
;     ...
;   f32x16 pA0, pA1, pB0, pB1; bf16x8 pa0, pa1, pa2, pa3; const int NT = seq / KVBLK;
;   SDMA(0, 0); DWAIT(); __syncthreads();
;   SDMA(1, KVBLK);
;   qkt3(pA0, pA1, K_lds, qr, r32, hi, cinit); partialSM3(pA0);
	v_ashrrev_i32_e32 v43, 4, v32
	v_bfe_u32 v48, v32, 2, 2
	v_cndmask_b32_e32 v0, v0, v1, vcc
	v_sqrt_f32_e32 v1, v0
	v_lshlrev_b32_e32 v42, 4, v32
	v_lshlrev_b32_e32 v52, 4, v245
	v_lshlrev_b32_e32 v53, 8, v10
	v_add_u32_e32 v2, -1, v1
	v_fma_f32 v3, -v2, v1, v0
	v_cmp_ge_f32_e64 s[40:41], 0, v3
	v_add_u32_e32 v3, 1, v1
	v_and_b32_e32 v54, 0xf0, v42
	v_cndmask_b32_e64 v2, v1, v2, s[40:41]
	v_fma_f32 v1, -v3, v1, v0
	v_cmp_lt_f32_e64 s[40:41], 0, v1
	v_xad_u32 v157, v54, v52, v53
	s_movk_i32 s16, 0xc0
	v_cndmask_b32_e64 v1, v2, v3, s[40:41]
	v_mul_f32_e32 v2, 0x37800000, v1
	v_cndmask_b32_e32 v1, v1, v2, vcc
	v_cmp_class_f32_e32 vcc, v0, v233
	v_mov_b32_e32 v55, v146
	v_mov_b32_e32 v56, v146
	v_cndmask_b32_e32 v0, v1, v0, vcc
	v_mul_f32_e32 v0, v145, v0
	v_fmamk_f32 v0, v0, 0x4136d45c, v234
	v_xor_b32_e32 v64, 0x80000000, v0
	v_lshlrev_b32_e32 v0, 3, v32
	v_and_b32_e32 v33, 24, v0
	v_add_u32_e32 v0, s88, v43
	v_xor_b32_e32 v2, v0, v32
	v_add_u32_e32 v1, 4, v0
	v_lshlrev_b32_e32 v2, 4, v2
	v_and_b32_e32 v44, 0xf0, v2
	v_xor_b32_e32 v2, v1, v32
	v_lshlrev_b32_e32 v2, 4, v2
	v_and_b32_e32 v45, 0xf0, v2
	v_lshl_or_b32 v2, v1, 9, v45
	v_add_u32_e32 v1, s89, v245
	v_add_u32_e32 v3, 2, v1
	v_lshlrev_b32_e32 v4, 1, v1
	v_and_b32_e32 v46, -16, v4
	v_lshlrev_b32_e32 v4, 1, v3
	v_and_b32_e32 v47, -16, v4
	v_lshrrev_b32_e32 v4, 1, v32
	v_and_b32_e32 v51, 4, v3
	v_and_b32_e32 v49, 8, v4
	v_and_b32_e32 v50, 4, v1
	v_or_b32_e32 v4, v51, v47
	v_or_b32_e32 v1, v50, v46
	v_or3_b32 v5, v4, v48, v49
	v_and_or_b32 v4, v32, s93, v33
	v_or3_b32 v1, v1, v48, v49
	v_lshlrev_b32_e32 v4, 1, v4
	v_lshl_or_b32 v4, v1, 9, v4
	v_lshlrev_b32_e32 v1, 5, v3
	v_and_or_b32 v1, v1, s93, v33
	v_lshl_or_b32 v0, v0, 9, v44
	v_lshlrev_b32_e32 v1, 1, v1
	v_lshl_or_b32 v6, v5, 9, v1
	v_ashrrev_i32_e32 v1, 31, v0
	v_lshl_add_u64 v[8:9], s[46:47], 0, v[0:1]
	v_ashrrev_i32_e32 v3, 31, v2
	global_load_lds_dwordx4 v[8:9], off
	v_lshl_add_u64 v[8:9], s[46:47], 0, v[2:3]
	s_add_i32 m0, s90, 0xc400
	v_ashrrev_i32_e32 v5, 31, v4
	global_load_lds_dwordx4 v[8:9], off
	v_lshl_add_u64 v[8:9], s[48:49], 0, v[4:5]
	s_mov_b32 m0, s90
	v_ashrrev_i32_e32 v7, 31, v6
	global_load_lds_dwordx4 v[8:9], off
	s_add_i32 m0, s90, 0x400
	s_add_u32 s40, s46, 0x8000
	s_addc_u32 s41, s47, 0
	v_lshl_add_u64 v[8:9], s[48:49], 0, v[6:7]
	s_add_u32 s46, s48, 0x8000
	global_load_lds_dwordx4 v[8:9], off
	s_addc_u32 s47, s49, 0
	v_lshl_add_u64 v[0:1], s[40:41], 0, v[0:1]
	s_add_i32 m0, s90, 0x10000
	s_waitcnt vmcnt(0)
	s_waitcnt vmcnt(0) lgkmcnt(0)
	s_barrier
	global_load_lds_dwordx4 v[0:1], off
	v_lshl_add_u64 v[0:1], s[40:41], 0, v[2:3]
	s_add_i32 m0, s90, 0x10400
	v_mov_b32_e32 v65, v64
	global_load_lds_dwordx4 v[0:1], off
	v_lshl_add_u64 v[0:1], s[46:47], 0, v[4:5]
	s_add_i32 m0, s90, 0x4000
	v_add_u32_e32 v4, 0, v157
	global_load_lds_dwordx4 v[0:1], off
	v_lshl_add_u64 v[0:1], s[46:47], 0, v[6:7]
	s_add_i32 m0, s90, 0x4400
	v_mov_b32_e32 v66, v64
	global_load_lds_dwordx4 v[0:1], off
	ds_read_b128 v[0:3], v4 offset:49152
	ds_read_b128 v[34:37], v4 offset:57344
	v_mov_b32_e32 v67, v64
	v_mov_b32_e32 v68, v64
	v_mov_b32_e32 v69, v64
	v_mov_b32_e32 v70, v64
	v_mov_b32_e32 v71, v64
	v_mov_b32_e32 v72, v64
	v_mov_b32_e32 v73, v64
	v_mov_b32_e32 v74, v64
	v_mov_b32_e32 v75, v64
	v_mov_b32_e32 v76, v64
	v_mov_b32_e32 v77, v64
	v_mov_b32_e32 v78, v64
	v_mov_b32_e32 v79, v64
	s_cmp_lg_u32 0, -1
	s_mov_b32 s46, 1
	s_waitcnt lgkmcnt(0)
	v_mfma_f32_32x32x16_bf16 v[16:31], v[0:3], v[140:143], v[64:79]
	s_mov_b32 s47, 2
	s_mov_b32 s48, 2
	v_mov_b32_e32 v57, v146
	v_mfma_f32_32x32x16_bf16 v[0:15], v[34:37], v[140:143], v[64:79]
	v_add_u32_e32 v34, 32, v52
	v_xad_u32 v177, v34, v54, v53
	v_add_u32_e32 v38, 0, v177
	ds_read_b128 v[34:37], v38 offset:49152
	ds_read_b128 v[38:41], v38 offset:57344
	s_waitcnt lgkmcnt(0)
	v_mfma_f32_32x32x16_bf16 v[16:31], v[34:37], v[136:139], v[16:31]
	v_add_u32_e32 v34, 64, v52
	v_xad_u32 v175, v34, v54, v53
	v_mfma_f32_32x32x16_bf16 v[0:15], v[38:41], v[136:139], v[0:15]
	v_add_u32_e32 v38, 0, v175
	ds_read_b128 v[34:37], v38 offset:49152
	ds_read_b128 v[38:41], v38 offset:57344
	s_waitcnt lgkmcnt(0)
	v_mfma_f32_32x32x16_bf16 v[16:31], v[34:37], v[132:135], v[16:31]
	v_add_u32_e32 v34, 0x60, v52
	v_xad_u32 v173, v34, v54, v53
	v_mfma_f32_32x32x16_bf16 v[0:15], v[38:41], v[132:135], v[0:15]
	v_add_u32_e32 v38, 0, v173
	ds_read_b128 v[34:37], v38 offset:49152
	ds_read_b128 v[38:41], v38 offset:57344
	s_waitcnt lgkmcnt(0)
	v_mfma_f32_32x32x16_bf16 v[16:31], v[34:37], v[128:131], v[16:31]
	v_add_u32_e32 v34, 0x80, v52
	v_xad_u32 v171, v34, v54, v53
	v_mfma_f32_32x32x16_bf16 v[0:15], v[38:41], v[128:131], v[0:15]
	v_add_u32_e32 v38, 0, v171
	ds_read_b128 v[34:37], v38 offset:49152
	ds_read_b128 v[38:41], v38 offset:57344
	s_waitcnt lgkmcnt(0)
	v_mfma_f32_32x32x16_bf16 v[16:31], v[34:37], v[124:127], v[16:31]
	v_add_u32_e32 v34, 0xa0, v52
	v_xad_u32 v169, v34, v54, v53
	v_mfma_f32_32x32x16_bf16 v[0:15], v[38:41], v[124:127], v[0:15]
	v_add_u32_e32 v38, 0, v169
	ds_read_b128 v[34:37], v38 offset:49152
	ds_read_b128 v[38:41], v38 offset:57344
	s_waitcnt lgkmcnt(0)
	v_mfma_f32_32x32x16_bf16 v[16:31], v[34:37], v[120:123], v[16:31]
	v_add_u32_e32 v34, 0xc0, v52
	v_xad_u32 v167, v34, v54, v53
	v_mfma_f32_32x32x16_bf16 v[0:15], v[38:41], v[120:123], v[0:15]
	v_add_u32_e32 v38, 0, v167
	ds_read_b128 v[34:37], v38 offset:49152
	ds_read_b128 v[38:41], v38 offset:57344
	s_waitcnt lgkmcnt(0)
	v_mfma_f32_32x32x16_bf16 v[16:31], v[34:37], v[116:119], v[16:31]
	v_add_u32_e32 v34, 0xe0, v52
	v_xad_u32 v159, v34, v54, v53
	v_mov_b32_e32 v52, v146
	v_mov_b32_e32 v53, v146
	v_mov_b32_e32 v54, v146
	v_mfma_f32_32x32x16_bf16 v[0:15], v[38:41], v[116:119], v[0:15]
	v_add_u32_e32 v38, 0, v159
	ds_read_b128 v[34:37], v38 offset:49152
	ds_read_b128 v[38:41], v38 offset:57344
	s_waitcnt vmcnt(0)
	s_waitcnt vmcnt(0) lgkmcnt(0)
	s_barrier
; #define SBAR() __builtin_amdgcn_sched_barrier(0)
; __device__ __forceinline__ void partialSM3(f32x16& p0) { for (int r = 0; r < 16; ++r) p0[r] = __builtin_amdgcn_exp2f(p0[r]); }
; __device__ __forceinline__ int v_rd_base2(int lane) { return ((lane & 3) << 3) | (((lane >> 2) & 3) << 6) | (((lane >> 4) & 1) << 5) | (((lane >> 5) & 1) << 11); }
; #define DWAIT() asm volatile("s_waitcnt vmcnt(0)" ::: "memory")
; __device__ __forceinline__ void attn_dense_body(const bf16* Qb, const bf16* __restrict__ Kh, const bf16* __restrict__ Vh, const bf16* __restrict__ Zb, ...
;     ...
;   const int vb0 = (int)(uintptr_t)V_lds + v_rd_base2(lane);
;   int koff0, koff1, voff0, voff1;
;   { const int rk0 = 8 * wid + (lane >> 4), rk1 = rk0 + 4; koff0 = rk0 * (LDK * 2) + (((lane & 15) ^ (rk0 & 15)) << 4); koff1 = rk1 * (LDK * 2) + (((lane & 15) ^ (rk1 & 15)) << 4);
;     const int st0 = 4 * wid + (lane >> 5), st1 = st0 + 2, q8 = (lane & 31) >> 2;
;     const int kk0 = ((st0 >> 2) << 3) | q8, kk1 = ((st1 >> 2) << 3) | q8;
;     const int ky0 = (kk0 & ~0xC) | ((kk0 & 4) << 1) | ((kk0 & 8) >> 1), ky1 = (kk1 & ~0xC) | ((kk1 & 4) << 1) | ((kk1 & 8) >> 1);
;     voff0 = ky0 * (LDK * 2) + ((st0 & 3) * 32 + (lane & 3) * 8) * 2; voff1 = ky1 * (LDK * 2) + ((st1 & 3) * 32 + (lane & 3) * 8) * 2; }
;     ...
;   f32x16 pA0, pA1, pB0, pB1; bf16x8 pa0, pa1, pa2, pa3; const int NT = seq / KVBLK;
;   SDMA(0, 0); DWAIT(); __syncthreads();
;   SDMA(1, KVBLK);
;   qkt3(pA0, pA1, K_lds, qr, r32, hi, cinit); partialSM3(pA0);
;   for (int r = 0; r < 16; ++r) pA1[r] = __builtin_amdgcn_exp2f(pA1[r]);
;   DWAIT(); __syncthreads();
;   int sP = 0, sC = 1, sN = 2;
;     ...
;   for (int j = 1; j + 1 < NT; j += 2) {
;     SDMA(sN, (j + 1) * KVBLK);
;     SBAR(); qkt3(pB0, pB1, KSLOT(sC), qr, r32, hi, cinit);
	v_mfma_f32_32x32x16_bf16 v[0:15], v[38:41], v[112:115], v[0:15]
	v_mov_b32_e32 v38, v146
	v_mov_b32_e32 v39, v146
	v_mov_b32_e32 v40, v146
	v_mov_b32_e32 v41, v146
	s_nop 7
	v_exp_f32_e32 v168, v0
	v_mfma_f32_32x32x16_bf16 v[16:31], v[34:37], v[112:115], v[16:31]
	v_exp_f32_e32 v156, v1
	v_or_b32_e32 v0, v47, v49
	v_add_u16_e32 v1, 2, v245
	v_lshlrev_b32_e32 v34, 1, v32
	v_or3_b32 v0, v0, v51, v48
	v_and_b32_e32 v1, 3, v1
	v_and_b32_e32 v35, 32, v34
	v_lshlrev_b32_e32 v32, 6, v32
	v_exp_f32_e32 v158, v2
	v_lshlrev_b32_e32 v0, 9, v0
	v_lshlrev_b32_e32 v1, 6, v1
	v_and_b32_e32 v2, 48, v42
	v_and_or_b32 v35, v42, s16, v35
	v_and_b32_e32 v32, 0x800, v32
	v_or3_b32 v148, v0, v1, v2
	v_or_b32_e32 v0, v46, v49
	v_or3_b32 v32, v35, v32, v33
	s_cselect_b32 s16, 0, 0
	s_lshl_b32 s15, s15, 6
	v_or3_b32 v0, v0, v50, v48
	v_add_u32_e32 v147, s16, v32
	v_exp_f32_e32 v179, v16
	v_exp_f32_e32 v170, v17
	v_exp_f32_e32 v172, v18
	v_exp_f32_e32 v174, v19
	v_exp_f32_e32 v184, v20
	v_exp_f32_e32 v186, v21
	v_exp_f32_e32 v188, v22
	v_exp_f32_e32 v190, v23
	v_exp_f32_e32 v206, v24
	v_exp_f32_e32 v200, v25
	v_exp_f32_e32 v202, v26
	v_exp_f32_e32 v204, v27
	v_exp_f32_e32 v216, v28
	v_exp_f32_e32 v218, v29
	v_exp_f32_e32 v220, v30
	v_exp_f32_e32 v222, v31
	v_exp_f32_e32 v166, v3
	v_exp_f32_e32 v176, v4
	v_exp_f32_e32 v178, v5
	v_exp_f32_e32 v180, v6
	v_exp_f32_e32 v182, v7
	v_exp_f32_e32 v198, v8
	v_exp_f32_e32 v196, v9
	v_exp_f32_e32 v192, v10
	v_exp_f32_e32 v194, v11
	v_exp_f32_e32 v208, v12
	v_exp_f32_e32 v210, v13
	v_exp_f32_e32 v212, v14
	v_exp_f32_e32 v214, v15
	s_mul_hi_i32 s16, s14, 0x820000
	s_mul_i32 s14, s14, 0x820000
	s_and_b32 s15, s15, 0x100
	v_lshlrev_b32_e32 v0, 9, v0
	v_and_b32_e32 v1, 0xc0, v34
	s_or_b32 s14, s14, s15
	v_or3_b32 v150, v0, v1, v2
	v_lshlrev_b32_e32 v0, 9, v43
	s_add_u32 s40, s42, s14
	v_add3_u32 v152, s92, v0, v45
	v_add3_u32 v154, s63, v0, v44
	v_ashrrev_i32_e32 v149, 31, v148
	s_addc_u32 s41, s43, s16
	v_ashrrev_i32_e32 v151, 31, v150
	v_ashrrev_i32_e32 v153, 31, v152
	v_ashrrev_i32_e32 v155, 31, v154
	v_mov_b32_e32 v0, 0
	v_mov_b32_e32 v1, v146
	v_mov_b32_e32 v2, v146
	v_mov_b32_e32 v3, v146
	v_mov_b32_e32 v4, v146
	v_mov_b32_e32 v5, v146
	v_mov_b32_e32 v6, v146
	v_mov_b32_e32 v7, v146
	v_mov_b32_e32 v8, v146
	v_mov_b32_e32 v9, v146
	v_mov_b32_e32 v10, v146
	v_mov_b32_e32 v11, v146
	v_mov_b32_e32 v12, v146
	v_mov_b32_e32 v13, v146
	v_mov_b32_e32 v14, v146
	v_mov_b32_e32 v15, v146
	v_mov_b32_e32 v16, 0
	v_mov_b32_e32 v17, v146
	v_mov_b32_e32 v18, v146
	v_mov_b32_e32 v19, v146
	v_mov_b32_e32 v20, v146
	v_mov_b32_e32 v21, v146
	v_mov_b32_e32 v22, v146
	v_mov_b32_e32 v23, v146
	v_mov_b32_e32 v24, v146
	v_mov_b32_e32 v25, v146
	v_mov_b32_e32 v26, v146
	v_mov_b32_e32 v27, v146
	v_mov_b32_e32 v28, v146
	v_mov_b32_e32 v29, v146
	v_mov_b32_e32 v30, v146
	v_mov_b32_e32 v31, v146
	v_mov_b32_e32 v32, 0
	v_mov_b32_e32 v33, v146
	v_mov_b32_e32 v34, v146
	v_mov_b32_e32 v35, v146
	v_mov_b32_e32 v36, v146
	v_mov_b32_e32 v37, v146
	v_mov_b32_e32 v42, v146
	v_mov_b32_e32 v43, v146
	v_mov_b32_e32 v44, v146
	v_mov_b32_e32 v45, v146
	v_mov_b32_e32 v46, v146
	v_mov_b32_e32 v47, v146
	v_mov_b32_e32 v48, 0
	v_mov_b32_e32 v49, v146
	v_mov_b32_e32 v50, v146
	v_mov_b32_e32 v51, v146
	s_add_u32 s84, s40, s58
	s_addc_u32 s85, s41, s59
	s_add_u32 s40, s40, s70
	s_addc_u32 s41, s41, s71
.LBB0_117:
	s_lshl_b32 s49, s48, 14
	s_mov_b32 s53, s46
	s_mov_b32 s46, s54
	s_add_i32 s86, s90, s49
	s_and_b32 s87, s47, 2
	s_lshl_b32 s87, s87, 14
	s_add_i32 s87, s87, s90
	s_lshl_b32 s15, s53, 14
	s_lshl_b32 s14, s54, 14
	v_add_u32_e32 v238, s15, v157
	ds_read_b128 v[246:249], v238 offset:49152
	ds_read_b128 v[238:241], v238 offset:57344
	v_add_u32_e32 v228, s15, v177
	ds_read_b128 v[224:227], v228 offset:49152
	ds_read_b128 v[228:231], v228 offset:57344
	v_cvt_pk_bf16_f32 v185, v202, v204
	v_cvt_pk_bf16_f32 v191, v180, v182
	v_cvt_pk_bf16_f32 v181, v212, v214
	v_cvt_pk_bf16_f32 v187, v220, v222
	v_cvt_pk_bf16_f32 v189, v158, v166
	s_waitcnt lgkmcnt(2)
	v_mfma_f32_32x32x16_bf16 v[96:111], v[246:249], v[140:143], v[64:79]
	v_mfma_f32_32x32x16_bf16 v[80:95], v[238:241], v[140:143], v[64:79]
	v_add_u32_e32 v238, s15, v175
	ds_read_b128 v[246:249], v238 offset:49152
	ds_read_b128 v[238:241], v238 offset:57344
	s_add_i32 m0, s86, 0xc000
	s_nop 0
	global_load_lds_dwordx4 v154, s[40:41]
	v_add_f32_e32 v162, 0, v179
	v_add_f32_e32 v162, v170, v162
	v_add_f32_e32 v162, v172, v162
	v_add_f32_e32 v162, v174, v162
	s_waitcnt lgkmcnt(2)
	v_mfma_f32_32x32x16_bf16 v[96:111], v[224:227], v[136:139], v[96:111]
	v_mfma_f32_32x32x16_bf16 v[80:95], v[228:231], v[136:139], v[80:95]
	v_add_u32_e32 v228, s15, v173
	ds_read_b128 v[224:227], v228 offset:49152
	ds_read_b128 v[228:231], v228 offset:57344
	s_add_i32 m0, s86, 0xc400
	s_nop 0
	global_load_lds_dwordx4 v152, s[40:41]
	s_add_u32 s40, s40, 0x8000
	s_addc_u32 s41, s41, 0
	v_add_f32_e32 v162, v184, v162
	v_add_f32_e32 v162, v186, v162
	v_add_f32_e32 v162, v188, v162
	v_add_f32_e32 v162, v190, v162
	s_waitcnt lgkmcnt(2)
	v_mfma_f32_32x32x16_bf16 v[96:111], v[246:249], v[132:135], v[96:111]
	v_mfma_f32_32x32x16_bf16 v[80:95], v[238:241], v[132:135], v[80:95]
	v_add_u32_e32 v238, s15, v171
	ds_read_b128 v[246:249], v238 offset:49152
	ds_read_b128 v[238:241], v238 offset:57344
	s_mov_b32 m0, s87
	s_nop 0
	global_load_lds_dwordx4 v150, s[84:85]
	v_add_f32_e32 v162, v206, v162
	v_add_f32_e32 v162, v200, v162
	v_add_f32_e32 v162, v202, v162
	v_add_f32_e32 v162, v204, v162
	s_waitcnt lgkmcnt(2)
; #define SBAR() __builtin_amdgcn_sched_barrier(0)
; #define PV_RD2(D0, X) const s16x4 X##l0 = tr_read<v_rd_off2(D0, 0, 0)>(vb), X##h0 = tr_read<v_rd_off2(D0, 0, 1)>(vb), X##l1 = tr_read<v_rd_off2(D0, 1, 0)>(vb), X##h1 = tr_read<v_rd_off2(D0, 1, 1)>(vb), \
;                               X##l2 = tr_read<v_rd_off2(D0, 2, 0)>(vb), X##h2 = tr_read<v_rd_off2(D0, 2, 1)>(vb), X##l3 = tr_read<v_rd_off2(D0, 3, 0)>(vb), X##h3 = tr_read<v_rd_off2(D0, 3, 1)>(vb)
; #define EXP4(P, B) do { P[(B) + 0] = __builtin_amdgcn_exp2f(P[(B) + 0]); P[(B) + 1] = __builtin_amdgcn_exp2f(P[(B) + 1]); P[(B) + 2] = __builtin_amdgcn_exp2f(P[(B) + 2]); P[(B) + 3] = __builtin_amdgcn_exp2f(P[(B) + 3]); } while (0)
; #define DWAIT() asm volatile("s_waitcnt vmcnt(0)" ::: "memory")
; #define ROT() do { const int t_ = sP; sP = sC; sC = sN; sN = t_; } while (0)
; __device__ __forceinline__ void pv_d03(f32x16* o, int vb, bf16x8 pa0, bf16x8 pa1, bf16x8 pa2, bf16x8 pa3, f32x16& pn, f32x16& pm) {
;   PV_RD2(0, a);
;   PV_RD2(1, b); asm volatile("s_waitcnt lgkmcnt(8)" ::: "memory"); SBAR(); PV_MM2(o[0], a); EXP4(pn, 0); EXP4(pm, 0); SBAR();
;   PV_RD2(2, c); asm volatile("s_waitcnt lgkmcnt(8)" ::: "memory"); SBAR(); PV_MM2(o[1], b); EXP4(pn, 4); EXP4(pm, 4); SBAR();
;   PV_RD2(3, d); asm volatile("s_waitcnt lgkmcnt(8)" ::: "memory"); SBAR(); PV_MM2(o[2], c); EXP4(pn, 8); EXP4(pm, 8); SBAR();
;   asm volatile("s_waitcnt lgkmcnt(0)" ::: "memory"); SBAR(); PV_MM2(o[3], d); EXP4(pn, 12); EXP4(pm, 12);
; }
; __device__ __forceinline__ void attn_dense_body(const bf16* Qb, const bf16* __restrict__ Kh, const bf16* __restrict__ Vh, const bf16* __restrict__ Zb, ...
;     ...
;     SBAR(); qkt3(pB0, pB1, KSLOT(sC), qr, r32, hi, cinit);
;     finishSM4<16>(pA0, pA1, l_reg, pa0, pa1, pa2, pa3);
;     pv_d03(o, vb0 + sP * (int)SHM_V, pa0, pa1, pa2, pa3, pB0, pB1);
;     DWAIT(); __syncthreads(); ROT();
	v_mfma_f32_32x32x16_bf16 v[96:111], v[224:227], v[128:131], v[96:111]
	v_mfma_f32_32x32x16_bf16 v[80:95], v[228:231], v[128:131], v[80:95]
	v_add_u32_e32 v228, s15, v169
	ds_read_b128 v[224:227], v228 offset:49152
	ds_read_b128 v[228:231], v228 offset:57344
	s_add_i32 m0, s87, 0x400
	s_nop 0
	global_load_lds_dwordx4 v148, s[84:85]
	s_add_u32 s84, s84, 0x8000
	s_addc_u32 s85, s85, 0
	v_add_f32_e32 v162, v216, v162
	v_add_f32_e32 v162, v218, v162
	v_add_f32_e32 v162, v220, v162
	v_add_f32_e32 v162, v222, v162
	s_waitcnt lgkmcnt(2)
	v_mfma_f32_32x32x16_bf16 v[96:111], v[246:249], v[124:127], v[96:111]
	v_mfma_f32_32x32x16_bf16 v[80:95], v[238:241], v[124:127], v[80:95]
	v_add_u32_e32 v238, s15, v167
	ds_read_b128 v[246:249], v238 offset:49152
	ds_read_b128 v[238:241], v238 offset:57344
	v_add_f32_e32 v162, v168, v162
	v_add_f32_e32 v162, v156, v162
	v_add_f32_e32 v162, v158, v162
	v_add_f32_e32 v162, v166, v162
	s_waitcnt lgkmcnt(2)
	v_mfma_f32_32x32x16_bf16 v[96:111], v[224:227], v[120:123], v[96:111]
	v_mfma_f32_32x32x16_bf16 v[80:95], v[228:231], v[120:123], v[80:95]
	v_add_u32_e32 v228, s15, v159
	ds_read_b128 v[224:227], v228 offset:49152
	ds_read_b128 v[228:231], v228 offset:57344
	v_add_f32_e32 v162, v176, v162
	v_add_f32_e32 v162, v178, v162
	v_add_f32_e32 v162, v180, v162
	v_add_f32_e32 v162, v182, v162
	s_waitcnt lgkmcnt(2)
	v_mfma_f32_32x32x16_bf16 v[96:111], v[246:249], v[116:119], v[96:111]
	v_mfma_f32_32x32x16_bf16 v[80:95], v[238:241], v[116:119], v[80:95]
	v_add_f32_e32 v162, v198, v162
	v_add_f32_e32 v162, v196, v162
	v_add_f32_e32 v162, v192, v162
	s_waitcnt lgkmcnt(0)
	v_mfma_f32_32x32x16_bf16 v[96:111], v[224:227], v[112:115], v[96:111]
	v_cvt_pk_bf16_f32 v238, v179, v170
	v_cvt_pk_bf16_f32 v179, v192, v194
	v_add_f32_e32 v162, v194, v162
	v_cvt_pk_bf16_f32 v241, v188, v190
	v_cvt_pk_bf16_f32 v190, v176, v178
	v_cvt_pk_bf16_f32 v178, v198, v196
	v_mfma_f32_32x32x16_bf16 v[80:95], v[228:231], v[112:115], v[80:95]
	s_bitcmp1_b32 s47, 1
	s_cselect_b32 s87, 0, 0x8000
	v_add_u32_e32 v246, s87, v147
	ds_read_b64_tr_b16 v[192:193], v246 offset:0
	ds_read_b64_tr_b16 v[194:195], v246 offset:0x100
	ds_read_b64_tr_b16 v[196:197], v246 offset:0x1000
	ds_read_b64_tr_b16 v[198:199], v246 offset:0x1100
	v_cvt_pk_bf16_f32 v240, v184, v186
	v_cvt_pk_bf16_f32 v184, v206, v200
	ds_read_b64_tr_b16 v[200:201], v246 offset:0x2000
	ds_read_b64_tr_b16 v[202:203], v246 offset:0x2100
	ds_read_b64_tr_b16 v[204:205], v246 offset:0x3000
	ds_read_b64_tr_b16 v[206:207], v246 offset:0x3100
	v_add_f32_e32 v162, v208, v162
	v_cvt_pk_bf16_f32 v180, v208, v210
	ds_read_b64_tr_b16 v[208:209], v246 offset:0x200
	v_add_f32_e32 v162, v210, v162
	ds_read_b64_tr_b16 v[210:211], v246 offset:0x300
	v_add_f32_e32 v162, v212, v162
	ds_read_b64_tr_b16 v[212:213], v246 offset:0x1200
	v_add_f32_e32 v162, v214, v162
	ds_read_b64_tr_b16 v[214:215], v246 offset:0x1300
	v_cvt_pk_bf16_f32 v186, v216, v218
	ds_read_b64_tr_b16 v[216:217], v246 offset:0x2200
	ds_read_b64_tr_b16 v[218:219], v246 offset:0x2300
	ds_read_b64_tr_b16 v[220:221], v246 offset:0x3200
	ds_read_b64_tr_b16 v[222:223], v246 offset:0x3300
	s_waitcnt lgkmcnt(8)
	v_add_f32_e32 v146, v146, v162
	v_cvt_pk_bf16_f32 v188, v168, v156
	v_cvt_pk_bf16_f32 v239, v172, v174
	s_nop 1
	v_mfma_f32_32x32x16_bf16 v[48:63], v[192:195], v[238:241], v[48:63]
	v_exp_f32_e32 v156, v96
	v_exp_f32_e32 v158, v97
	v_exp_f32_e32 v166, v82
	v_exp_f32_e32 v168, v83
	v_exp_f32_e32 v162, v98
	v_exp_f32_e32 v163, v99
	v_exp_f32_e32 v164, v80
	v_mfma_f32_32x32x16_bf16 v[48:63], v[196:199], v[184:187], v[48:63]
	v_exp_f32_e32 v165, v81
	v_mfma_f32_32x32x16_bf16 v[48:63], v[200:203], v[188:191], v[48:63]
	v_mfma_f32_32x32x16_bf16 v[48:63], v[204:207], v[178:181], v[48:63]
	ds_read_b64_tr_b16 v[80:81], v246 offset:0x400
	ds_read_b64_tr_b16 v[82:83], v246 offset:0x500
	ds_read_b64_tr_b16 v[96:97], v246 offset:0x1400
	ds_read_b64_tr_b16 v[98:99], v246 offset:0x1500
	ds_read_b64_tr_b16 v[192:193], v246 offset:0x2400
	ds_read_b64_tr_b16 v[194:195], v246 offset:0x2500
	ds_read_b64_tr_b16 v[196:197], v246 offset:0x3400
	ds_read_b64_tr_b16 v[198:199], v246 offset:0x3500
	s_waitcnt lgkmcnt(8)
	v_mfma_f32_32x32x16_bf16 v[32:47], v[208:211], v[238:241], v[32:47]
	v_exp_f32_e32 v170, v100
	v_exp_f32_e32 v172, v101
	v_exp_f32_e32 v174, v102
	v_exp_f32_e32 v176, v103
	v_mfma_f32_32x32x16_bf16 v[32:47], v[212:215], v[184:187], v[32:47]
	v_mfma_f32_32x32x16_bf16 v[32:47], v[216:219], v[188:191], v[32:47]
	v_exp_f32_e32 v216, v84
	v_exp_f32_e32 v218, v86
	v_exp_f32_e32 v217, v85
	v_exp_f32_e32 v219, v87
	v_mfma_f32_32x32x16_bf16 v[32:47], v[220:223], v[178:181], v[32:47]
	ds_read_b64_tr_b16 v[84:85], v246 offset:0x600
	ds_read_b64_tr_b16 v[86:87], v246 offset:0x700
	ds_read_b64_tr_b16 v[100:101], v246 offset:0x1600
	ds_read_b64_tr_b16 v[102:103], v246 offset:0x1700
	ds_read_b64_tr_b16 v[200:201], v246 offset:0x2600
	ds_read_b64_tr_b16 v[202:203], v246 offset:0x2700
	ds_read_b64_tr_b16 v[204:205], v246 offset:0x3600
	ds_read_b64_tr_b16 v[206:207], v246 offset:0x3700
	s_waitcnt lgkmcnt(8)
	v_mfma_f32_32x32x16_bf16 v[16:31], v[80:83], v[238:241], v[16:31]
	v_exp_f32_e32 v220, v88
	v_exp_f32_e32 v222, v90
	v_exp_f32_e32 v221, v89
	v_exp_f32_e32 v223, v91
	v_mfma_f32_32x32x16_bf16 v[16:31], v[96:99], v[184:187], v[16:31]
	v_mfma_f32_32x32x16_bf16 v[16:31], v[192:195], v[188:191], v[16:31]
	v_exp_f32_e32 v192, v104
	v_exp_f32_e32 v194, v106
	v_exp_f32_e32 v193, v105
	v_exp_f32_e32 v195, v107
	v_mfma_f32_32x32x16_bf16 v[16:31], v[196:199], v[178:181], v[16:31]
	s_waitcnt lgkmcnt(0)
	s_waitcnt vmcnt(2)
	s_barrier
; #define SBAR() __builtin_amdgcn_sched_barrier(0)
; __device__ __forceinline__ void attn_dense_body(const bf16* Qb, const bf16* __restrict__ Kh, const bf16* __restrict__ Vh, const bf16* __restrict__ Zb, ...
;     ...
;     SDMA(sN, (j + 2) * KVBLK);
;     SBAR(); qkt3(pA0, pA1, KSLOT(sC), qr, r32, hi, cinit);
;     finishSM4<16>(pB0, pB1, l_reg, pa0, pa1, pa2, pa3);
;     pv_d03(o, vb0 + sP * (int)SHM_V, pa0, pa1, pa2, pa3, pA0, pA1);
	s_add_i32 s86, s90, s14
	s_mov_b32 s87, 0x4000
	s_bitcmp1_b32 s47, 1
	s_cselect_b32 s87, 0x18000, s87
	s_add_i32 s87, s87, s90
	v_mfma_f32_32x32x16_bf16 v[0:15], v[84:87], v[238:241], v[0:15]
	v_exp_f32_e32 v196, v94
	v_mfma_f32_32x32x16_bf16 v[0:15], v[100:103], v[184:187], v[0:15]
	v_exp_f32_e32 v186, v108
	v_exp_f32_e32 v187, v109
	v_exp_f32_e32 v197, v95
	v_mfma_f32_32x32x16_bf16 v[0:15], v[200:203], v[188:191], v[0:15]
	v_exp_f32_e32 v188, v110
	v_exp_f32_e32 v190, v92
	v_exp_f32_e32 v189, v111
	v_exp_f32_e32 v191, v93
	v_mfma_f32_32x32x16_bf16 v[0:15], v[204:207], v[178:181], v[0:15]
	s_add_i32 s16, s49, 0
	v_add_u32_e32 v182, s16, v157
	ds_read_b128 v[178:181], v182 offset:49152
	ds_read_b128 v[182:185], v182 offset:57344
	v_add_u32_e32 v246, s16, v177
	ds_read_b128 v[238:241], v246 offset:49152
	ds_read_b128 v[246:249], v246 offset:57344
	s_mov_b32 s17, 0x18000
	s_bitcmp1_b32 s47, 1
	s_cselect_b32 s17, 0x4000, s17
	v_add_u32_e32 v206, s17, v147
	v_cvt_pk_bf16_f32 v214, v186, v187
	v_cvt_pk_bf16_f32 v215, v188, v189
	v_cvt_pk_bf16_f32 v230, v190, v191
	v_cvt_pk_bf16_f32 v212, v192, v193
	s_waitcnt lgkmcnt(2)
	v_mfma_f32_32x32x16_bf16 v[96:111], v[178:181], v[140:143], v[64:79]
	v_mfma_f32_32x32x16_bf16 v[80:95], v[182:185], v[140:143], v[64:79]
	v_add_u32_e32 v182, s16, v175
	ds_read_b128 v[178:181], v182 offset:49152
	ds_read_b128 v[182:185], v182 offset:57344
	s_add_i32 m0, s86, 0xc000
	s_nop 0
	global_load_lds_dwordx4 v154, s[40:41]
	v_cvt_pk_bf16_f32 v213, v194, v195
	v_cvt_pk_bf16_f32 v231, v196, v197
	v_cvt_pk_bf16_f32 v226, v216, v217
	s_waitcnt lgkmcnt(2)
	v_mfma_f32_32x32x16_bf16 v[96:111], v[238:241], v[136:139], v[96:111]
	v_mfma_f32_32x32x16_bf16 v[80:95], v[246:249], v[136:139], v[80:95]
	v_add_u32_e32 v246, s16, v173
	ds_read_b128 v[238:241], v246 offset:49152
	ds_read_b128 v[246:249], v246 offset:57344
	s_add_i32 m0, s86, 0xc400
	s_nop 0
	global_load_lds_dwordx4 v152, s[40:41]
	s_add_u32 s40, s40, 0x8000
	s_addc_u32 s41, s41, 0
	v_cvt_pk_bf16_f32 v227, v218, v219
	v_cvt_pk_bf16_f32 v208, v156, v158
	v_cvt_pk_bf16_f32 v210, v170, v172
	s_waitcnt lgkmcnt(2)
	v_mfma_f32_32x32x16_bf16 v[96:111], v[178:181], v[132:135], v[96:111]
	v_mfma_f32_32x32x16_bf16 v[80:95], v[182:185], v[132:135], v[80:95]
	v_add_u32_e32 v182, s16, v171
	ds_read_b128 v[178:181], v182 offset:49152
	ds_read_b128 v[182:185], v182 offset:57344
	s_mov_b32 m0, s87
	s_nop 0
	global_load_lds_dwordx4 v150, s[84:85]
	v_cvt_pk_bf16_f32 v209, v162, v163
	v_cvt_pk_bf16_f32 v211, v174, v176
	v_cvt_pk_bf16_f32 v224, v164, v165
	s_waitcnt lgkmcnt(2)
	v_mfma_f32_32x32x16_bf16 v[96:111], v[238:241], v[128:131], v[96:111]
	v_mfma_f32_32x32x16_bf16 v[80:95], v[246:249], v[128:131], v[80:95]
	v_add_u32_e32 v246, s16, v169
	ds_read_b128 v[238:241], v246 offset:49152
	ds_read_b128 v[246:249], v246 offset:57344
	s_add_i32 m0, s87, 0x400
	s_nop 0
	global_load_lds_dwordx4 v148, s[84:85]
	s_add_u32 s84, s84, 0x8000
	s_addc_u32 s85, s85, 0
	v_cvt_pk_bf16_f32 v225, v166, v168
	v_cvt_pk_bf16_f32 v228, v220, v221
	v_cvt_pk_bf16_f32 v229, v222, v223
	s_waitcnt lgkmcnt(2)
	v_mfma_f32_32x32x16_bf16 v[96:111], v[178:181], v[124:127], v[96:111]
	v_mfma_f32_32x32x16_bf16 v[80:95], v[182:185], v[124:127], v[80:95]
	v_add_u32_e32 v182, s16, v167
	ds_read_b128 v[178:181], v182 offset:49152
	ds_read_b128 v[182:185], v182 offset:57344
	s_waitcnt lgkmcnt(2)
	v_mfma_f32_32x32x16_bf16 v[96:111], v[238:241], v[120:123], v[96:111]
	v_mfma_f32_32x32x16_bf16 v[80:95], v[246:249], v[120:123], v[80:95]
	v_add_u32_e32 v246, s16, v159
	ds_read_b128 v[238:241], v246 offset:49152
	ds_read_b128 v[246:249], v246 offset:57344
	s_waitcnt lgkmcnt(2)
	v_mfma_f32_32x32x16_bf16 v[96:111], v[178:181], v[116:119], v[96:111]
	v_mfma_f32_32x32x16_bf16 v[80:95], v[182:185], v[116:119], v[80:95]
	v_add_f32_e32 v178, 0, v156
	v_add_f32_e32 v178, v158, v178
	v_add_f32_e32 v178, v162, v178
	v_add_f32_e32 v178, v163, v178
	v_add_f32_e32 v178, v170, v178
	v_add_f32_e32 v178, v172, v178
	v_add_f32_e32 v178, v174, v178
	v_add_f32_e32 v178, v176, v178
	v_add_f32_e32 v178, v192, v178
	v_add_f32_e32 v178, v193, v178
	v_add_f32_e32 v178, v194, v178
	v_add_f32_e32 v178, v195, v178
	v_add_f32_e32 v178, v186, v178
	v_add_f32_e32 v178, v187, v178
	v_add_f32_e32 v178, v188, v178
	v_add_f32_e32 v178, v189, v178
	s_waitcnt lgkmcnt(0)
	v_mfma_f32_32x32x16_bf16 v[96:111], v[238:241], v[112:115], v[96:111]
	v_add_f32_e32 v178, v164, v178
	v_add_f32_e32 v178, v165, v178
	v_add_f32_e32 v178, v166, v178
	v_add_f32_e32 v178, v168, v178
	v_add_f32_e32 v178, v216, v178
	v_add_f32_e32 v178, v217, v178
	v_add_f32_e32 v178, v218, v178
	v_add_f32_e32 v178, v219, v178
	v_add_f32_e32 v178, v220, v178
	v_add_f32_e32 v178, v221, v178
	v_add_f32_e32 v178, v222, v178
	v_add_f32_e32 v178, v223, v178
	v_add_f32_e32 v178, v190, v178
	v_add_f32_e32 v178, v191, v178
	v_add_f32_e32 v178, v196, v178
	v_add_f32_e32 v178, v197, v178
	v_add_f32_e32 v146, v146, v178
	ds_read_b64_tr_b16 v[178:179], v206 offset:0
	ds_read_b64_tr_b16 v[180:181], v206 offset:0x100
	v_mfma_f32_32x32x16_bf16 v[80:95], v[246:249], v[112:115], v[80:95]
	ds_read_b64_tr_b16 v[182:183], v206 offset:0x1000
	ds_read_b64_tr_b16 v[184:185], v206 offset:0x1100
	ds_read_b64_tr_b16 v[186:187], v206 offset:0x2000
	ds_read_b64_tr_b16 v[188:189], v206 offset:0x2100
	ds_read_b64_tr_b16 v[190:191], v206 offset:0x3000
	ds_read_b64_tr_b16 v[192:193], v206 offset:0x3100
	ds_read_b64_tr_b16 v[194:195], v206 offset:0x200
	ds_read_b64_tr_b16 v[196:197], v206 offset:0x300
	ds_read_b64_tr_b16 v[198:199], v206 offset:0x1200
	ds_read_b64_tr_b16 v[200:201], v206 offset:0x1300
	ds_read_b64_tr_b16 v[202:203], v206 offset:0x2200
	ds_read_b64_tr_b16 v[204:205], v206 offset:0x2300
	ds_read_b64_tr_b16 v[216:217], v206 offset:0x3200
	ds_read_b64_tr_b16 v[218:219], v206 offset:0x3300
	s_waitcnt lgkmcnt(8)
; #define SBAR() __builtin_amdgcn_sched_barrier(0)
; #define DWAIT() asm volatile("s_waitcnt vmcnt(0)" ::: "memory")
; #define ROT() do { const int t_ = sP; sP = sC; sC = sN; sN = t_; } while (0)
; __device__ __forceinline__ void attn_dense_body(const bf16* Qb, const bf16* __restrict__ Kh, const bf16* __restrict__ Vh, const bf16* __restrict__ Zb, ...
;     ...
;     pv_d03(o, vb0 + sP * (int)SHM_V, pa0, pa1, pa2, pa3, pA0, pA1);
;     DWAIT(); __syncthreads(); ROT();
;   }
;   SBAR(); qkt3(pB0, pB1, KSLOT(sC), qr, r32, hi, cinit);
	v_mfma_f32_32x32x16_bf16 v[48:63], v[178:181], v[208:211], v[48:63]
	v_exp_f32_e32 v179, v96
	v_exp_f32_e32 v170, v97
	v_exp_f32_e32 v172, v98
	v_exp_f32_e32 v174, v99
	s_nop 6
	v_exp_f32_e32 v168, v80
	v_exp_f32_e32 v156, v81
	v_exp_f32_e32 v158, v82
	v_mfma_f32_32x32x16_bf16 v[48:63], v[182:185], v[212:215], v[48:63]
	v_exp_f32_e32 v166, v83
	v_mfma_f32_32x32x16_bf16 v[48:63], v[186:189], v[224:227], v[48:63]
	v_mfma_f32_32x32x16_bf16 v[48:63], v[190:193], v[228:231], v[48:63]
	ds_read_b64_tr_b16 v[80:81], v206 offset:0x400
	ds_read_b64_tr_b16 v[82:83], v206 offset:0x500
	ds_read_b64_tr_b16 v[96:97], v206 offset:0x1400
	ds_read_b64_tr_b16 v[98:99], v206 offset:0x1500
	ds_read_b64_tr_b16 v[220:221], v206 offset:0x2400
	ds_read_b64_tr_b16 v[222:223], v206 offset:0x2500
	ds_read_b64_tr_b16 v[238:239], v206 offset:0x3400
	ds_read_b64_tr_b16 v[240:241], v206 offset:0x3500
	s_waitcnt lgkmcnt(8)
	v_mfma_f32_32x32x16_bf16 v[32:47], v[194:197], v[208:211], v[32:47]
	v_exp_f32_e32 v184, v100
	v_exp_f32_e32 v186, v101
	v_exp_f32_e32 v188, v102
	v_exp_f32_e32 v190, v103
	v_exp_f32_e32 v176, v84
	v_exp_f32_e32 v178, v85
	v_exp_f32_e32 v180, v86
	v_mfma_f32_32x32x16_bf16 v[32:47], v[198:201], v[212:215], v[32:47]
	v_exp_f32_e32 v182, v87
	v_mfma_f32_32x32x16_bf16 v[32:47], v[202:205], v[224:227], v[32:47]
	v_mfma_f32_32x32x16_bf16 v[32:47], v[216:219], v[228:231], v[32:47]
	ds_read_b64_tr_b16 v[84:85], v206 offset:0x600
	ds_read_b64_tr_b16 v[86:87], v206 offset:0x700
	ds_read_b64_tr_b16 v[100:101], v206 offset:0x1600
	ds_read_b64_tr_b16 v[102:103], v206 offset:0x1700
	ds_read_b64_tr_b16 v[248:249], v206 offset:0x2600
	ds_read_b64_tr_b16 v[250:251], v206 offset:0x2700
	ds_read_b64_tr_b16 v[162:163], v206 offset:0x3600
	ds_read_b64_tr_b16 v[164:165], v206 offset:0x3700
	s_waitcnt lgkmcnt(8)
	v_mfma_f32_32x32x16_bf16 v[16:31], v[80:83], v[208:211], v[16:31]
	v_exp_f32_e32 v206, v104
	v_exp_f32_e32 v200, v105
	v_exp_f32_e32 v202, v106
	v_exp_f32_e32 v204, v107
	v_exp_f32_e32 v198, v88
	v_exp_f32_e32 v196, v89
	v_exp_f32_e32 v192, v90
	v_mfma_f32_32x32x16_bf16 v[16:31], v[96:99], v[212:215], v[16:31]
	v_exp_f32_e32 v194, v91
	v_mfma_f32_32x32x16_bf16 v[16:31], v[220:223], v[224:227], v[16:31]
	v_mfma_f32_32x32x16_bf16 v[16:31], v[238:241], v[228:231], v[16:31]
	s_waitcnt lgkmcnt(0)
	v_mfma_f32_32x32x16_bf16 v[0:15], v[84:87], v[208:211], v[0:15]
	v_exp_f32_e32 v216, v108
	v_exp_f32_e32 v218, v109
	v_exp_f32_e32 v220, v110
	v_exp_f32_e32 v222, v111
	v_exp_f32_e32 v208, v92
	v_exp_f32_e32 v210, v93
	v_mfma_f32_32x32x16_bf16 v[0:15], v[100:103], v[212:215], v[0:15]
	v_exp_f32_e32 v212, v94
	v_exp_f32_e32 v214, v95
	s_add_i32 s47, s47, 2
	s_mov_b32 s54, s48
	s_mov_b32 s48, s53
	v_mfma_f32_32x32x16_bf16 v[0:15], v[248:251], v[224:227], v[0:15]
	s_waitcnt vmcnt(2)
	s_barrier
	s_cmp_lt_u32 s47, s52
	v_mfma_f32_32x32x16_bf16 v[0:15], v[162:165], v[228:231], v[0:15]
	s_cbranch_scc1 .LBB0_117
	s_add_u32 s40, s36, s44
	s_addc_u32 s41, s50, s45
	s_add_i32 s14, s14, 0
	v_add_u32_e32 v100, s14, v157
	ds_read_b128 v[96:99], v100 offset:49152
	v_add_u32_e32 v104, s14, v159
	v_add_f32_e32 v148, 0, v179
	v_cvt_pk_bf16_f32 v108, v179, v170
	v_cvt_pk_bf16_f32 v109, v172, v174
	v_cvt_pk_bf16_f32 v110, v184, v186
	v_cvt_pk_bf16_f32 v111, v188, v190
	s_waitcnt lgkmcnt(0)
	v_mfma_f32_32x32x16_bf16 v[80:95], v[96:99], v[140:143], v[64:79]
	ds_read_b128 v[96:99], v100 offset:57344
	v_add_u32_e32 v100, s14, v177
	s_waitcnt lgkmcnt(0)
	v_mfma_f32_32x32x16_bf16 v[64:79], v[96:99], v[140:143], v[64:79]
	ds_read_b128 v[96:99], v100 offset:49152
	s_waitcnt lgkmcnt(0)
	v_mfma_f32_32x32x16_bf16 v[80:95], v[96:99], v[136:139], v[80:95]
	ds_read_b128 v[96:99], v100 offset:57344
	v_add_u32_e32 v100, s14, v175
	s_waitcnt lgkmcnt(0)
	v_mfma_f32_32x32x16_bf16 v[64:79], v[96:99], v[136:139], v[64:79]
	ds_read_b128 v[96:99], v100 offset:49152
	s_waitcnt lgkmcnt(0)
	v_mfma_f32_32x32x16_bf16 v[80:95], v[96:99], v[132:135], v[80:95]
	ds_read_b128 v[96:99], v100 offset:57344
	v_add_u32_e32 v100, s14, v173
	s_waitcnt lgkmcnt(0)
	v_mfma_f32_32x32x16_bf16 v[64:79], v[96:99], v[132:135], v[64:79]
	ds_read_b128 v[96:99], v100 offset:49152
	s_waitcnt lgkmcnt(0)
	v_mfma_f32_32x32x16_bf16 v[80:95], v[96:99], v[128:131], v[80:95]
	ds_read_b128 v[96:99], v100 offset:57344
	v_add_u32_e32 v100, s14, v171
	s_waitcnt lgkmcnt(0)
	v_mfma_f32_32x32x16_bf16 v[64:79], v[96:99], v[128:131], v[64:79]
	ds_read_b128 v[96:99], v100 offset:49152
	s_waitcnt lgkmcnt(0)
	v_mfma_f32_32x32x16_bf16 v[80:95], v[96:99], v[124:127], v[80:95]
	ds_read_b128 v[96:99], v100 offset:57344
	v_add_u32_e32 v100, s14, v169
	s_waitcnt lgkmcnt(0)
	v_mfma_f32_32x32x16_bf16 v[64:79], v[96:99], v[124:127], v[64:79]
	ds_read_b128 v[96:99], v100 offset:49152
	s_waitcnt lgkmcnt(0)
	v_mfma_f32_32x32x16_bf16 v[80:95], v[96:99], v[120:123], v[80:95]
	ds_read_b128 v[96:99], v100 offset:57344
	v_add_u32_e32 v100, s14, v167
	s_waitcnt lgkmcnt(0)
	v_mfma_f32_32x32x16_bf16 v[64:79], v[96:99], v[120:123], v[64:79]
	ds_read_b128 v[96:99], v100 offset:49152
	s_waitcnt lgkmcnt(0)
	v_mfma_f32_32x32x16_bf16 v[80:95], v[96:99], v[116:119], v[80:95]
	ds_read_b128 v[96:99], v100 offset:57344
	ds_read_b128 v[100:103], v104 offset:49152
	ds_read_b128 v[104:107], v104 offset:57344
	s_waitcnt lgkmcnt(2)
	v_mfma_f32_32x32x16_bf16 v[64:79], v[96:99], v[116:119], v[64:79]
	v_cvt_pk_bf16_f32 v96, v206, v200
	v_cvt_pk_bf16_f32 v97, v202, v204
	v_cvt_pk_bf16_f32 v98, v216, v218
	v_cvt_pk_bf16_f32 v99, v220, v222
	v_cvt_pk_bf16_f32 v116, v198, v196
	v_cvt_pk_bf16_f32 v117, v192, v194
	v_cvt_pk_bf16_f32 v118, v208, v210
	s_waitcnt lgkmcnt(1)
; #define SBAR() __builtin_amdgcn_sched_barrier(0)
; __device__ __forceinline__ void attn_dense_body(const bf16* Qb, const bf16* __restrict__ Kh, const bf16* __restrict__ Vh, const bf16* __restrict__ Zb, ...
;     ...
;   SBAR(); qkt3(pB0, pB1, KSLOT(sC), qr, r32, hi, cinit);
;   finishSM4<16>(pA0, pA1, l_reg, pa0, pa1, pa2, pa3); SBAR();
;   pv_d03(o, vb0 + sP * (int)SHM_V, pa0, pa1, pa2, pa3, pB0, pB1);
;   finishSM4<16>(pB0, pB1, l_reg, pa0, pa1, pa2, pa3); SBAR();
	v_mfma_f32_32x32x16_bf16 v[80:95], v[100:103], v[112:115], v[80:95]
	v_cvt_pk_bf16_f32 v100, v168, v156
	v_cvt_pk_bf16_f32 v101, v158, v166
	v_cvt_pk_bf16_f32 v102, v176, v178
	v_cvt_pk_bf16_f32 v103, v180, v182
	v_cvt_pk_bf16_f32 v119, v212, v214
	s_waitcnt lgkmcnt(0)
	v_mfma_f32_32x32x16_bf16 v[64:79], v[104:107], v[112:115], v[64:79]
	s_mov_b32 s87, 0x18000
	s_bitcmp1_b32 s52, 1
	s_cselect_b32 s87, 0x4000, s87
	v_add_u32_e32 v246, s87, v147
	s_bitcmp1_b32 s52, 1
	s_cselect_b32 s87, 0, 0x8000
	v_add_u32_e32 v147, s87, v147
	ds_read_b64_tr_b16 v[104:105], v147 offset:0
	ds_read_b64_tr_b16 v[106:107], v147 offset:0x100
	ds_read_b64_tr_b16 v[112:113], v147 offset:0x1000
	ds_read_b64_tr_b16 v[114:115], v147 offset:0x1100
	ds_read_b64_tr_b16 v[120:121], v147 offset:0x2000
	ds_read_b64_tr_b16 v[122:123], v147 offset:0x2100
	ds_read_b64_tr_b16 v[124:125], v147 offset:0x3000
	ds_read_b64_tr_b16 v[126:127], v147 offset:0x3100
	ds_read_b64_tr_b16 v[128:129], v147 offset:0x200
	ds_read_b64_tr_b16 v[130:131], v147 offset:0x300
	ds_read_b64_tr_b16 v[132:133], v147 offset:0x1200
	ds_read_b64_tr_b16 v[134:135], v147 offset:0x1300
	ds_read_b64_tr_b16 v[136:137], v147 offset:0x2200
	ds_read_b64_tr_b16 v[138:139], v147 offset:0x2300
	ds_read_b64_tr_b16 v[140:141], v147 offset:0x3200
	ds_read_b64_tr_b16 v[142:143], v147 offset:0x3300
	s_waitcnt lgkmcnt(8)
	s_nop 0
	v_mfma_f32_32x32x16_bf16 v[48:63], v[104:107], v[108:111], v[48:63]
	s_nop 1
	v_exp_f32_e32 v171, v80
	v_exp_f32_e32 v173, v81
	v_exp_f32_e32 v175, v82
	v_exp_f32_e32 v185, v83
	s_nop 2
	v_exp_f32_e32 v157, v64
	v_exp_f32_e32 v159, v65
	v_exp_f32_e32 v167, v66
	v_mfma_f32_32x32x16_bf16 v[48:63], v[112:115], v[96:99], v[48:63]
	v_exp_f32_e32 v177, v67
	v_mfma_f32_32x32x16_bf16 v[48:63], v[120:123], v[100:103], v[48:63]
	v_mfma_f32_32x32x16_bf16 v[48:63], v[124:127], v[116:119], v[48:63]
	ds_read_b64_tr_b16 v[64:65], v147 offset:0x400
	ds_read_b64_tr_b16 v[66:67], v147 offset:0x500
	ds_read_b64_tr_b16 v[80:81], v147 offset:0x1400
	ds_read_b64_tr_b16 v[82:83], v147 offset:0x1500
	ds_read_b64_tr_b16 v[104:105], v147 offset:0x2400
	ds_read_b64_tr_b16 v[106:107], v147 offset:0x2500
	ds_read_b64_tr_b16 v[112:113], v147 offset:0x3400
	ds_read_b64_tr_b16 v[114:115], v147 offset:0x3500
	s_waitcnt lgkmcnt(8)
	v_mfma_f32_32x32x16_bf16 v[32:47], v[128:131], v[108:111], v[32:47]
	v_exp_f32_e32 v187, v84
	v_exp_f32_e32 v189, v85
	v_exp_f32_e32 v191, v86
	v_exp_f32_e32 v207, v87
	v_exp_f32_e32 v179, v68
	v_exp_f32_e32 v181, v69
	v_exp_f32_e32 v183, v70
	v_mfma_f32_32x32x16_bf16 v[32:47], v[132:135], v[96:99], v[32:47]
	v_exp_f32_e32 v199, v71
	v_mfma_f32_32x32x16_bf16 v[32:47], v[136:139], v[100:103], v[32:47]
	v_mfma_f32_32x32x16_bf16 v[32:47], v[140:143], v[116:119], v[32:47]
	ds_read_b64_tr_b16 v[68:69], v147 offset:0x600
	ds_read_b64_tr_b16 v[70:71], v147 offset:0x700
	ds_read_b64_tr_b16 v[84:85], v147 offset:0x1600
	ds_read_b64_tr_b16 v[86:87], v147 offset:0x1700
	ds_read_b64_tr_b16 v[120:121], v147 offset:0x2600
	ds_read_b64_tr_b16 v[122:123], v147 offset:0x2700
	ds_read_b64_tr_b16 v[124:125], v147 offset:0x3600
	ds_read_b64_tr_b16 v[126:127], v147 offset:0x3700
	s_waitcnt lgkmcnt(8)
	v_mfma_f32_32x32x16_bf16 v[16:31], v[64:67], v[108:111], v[16:31]
	v_exp_f32_e32 v201, v88
	v_exp_f32_e32 v203, v89
	v_exp_f32_e32 v205, v90
	v_exp_f32_e32 v217, v91
	v_exp_f32_e32 v197, v72
	v_exp_f32_e32 v193, v73
	v_exp_f32_e32 v195, v74
	v_mfma_f32_32x32x16_bf16 v[16:31], v[80:83], v[96:99], v[16:31]
	v_exp_f32_e32 v209, v75
	v_mfma_f32_32x32x16_bf16 v[16:31], v[104:107], v[100:103], v[16:31]
	v_mfma_f32_32x32x16_bf16 v[16:31], v[112:115], v[116:119], v[16:31]
	s_waitcnt lgkmcnt(0)
	v_mov_b32_e32 v149, v161
	v_add_f32_e64 v64, v170, v148
	v_add_f32_e64 v65, v171, v149
	v_mfma_f32_32x32x16_bf16 v[0:15], v[68:71], v[108:111], v[0:15]
	v_add_f32_e64 v64, v172, v64
	v_add_f32_e64 v65, v173, v65
	v_exp_f32_e32 v219, v92
	v_pk_add_f32 v[64:65], v[174:175], v[64:65]
	v_exp_f32_e32 v221, v93
	v_pk_add_f32 v[64:65], v[184:185], v[64:65]
	v_exp_f32_e32 v223, v94
	v_pk_add_f32 v[64:65], v[186:187], v[64:65]
	v_exp_f32_e32 v169, v95
	v_pk_add_f32 v[64:65], v[188:189], v[64:65]
	v_mfma_f32_32x32x16_bf16 v[0:15], v[84:87], v[96:99], v[0:15]
	v_add_f32_e64 v64, v190, v64
	v_add_f32_e64 v65, v191, v65
	v_exp_f32_e32 v211, v76
	v_pk_add_f32 v[64:65], v[206:207], v[64:65]
	v_exp_f32_e32 v213, v77
	v_pk_add_f32 v[64:65], v[200:201], v[64:65]
	v_exp_f32_e32 v215, v78
	v_pk_add_f32 v[64:65], v[202:203], v[64:65]
	v_mfma_f32_32x32x16_bf16 v[0:15], v[120:123], v[100:103], v[0:15]
	v_add_f32_e64 v64, v204, v64
	v_add_f32_e64 v65, v205, v65
	v_exp_f32_e32 v147, v79
	v_pk_add_f32 v[64:65], v[216:217], v[64:65]
	v_cvt_pk_bf16_f32 v66, v187, v189
	v_pk_add_f32 v[64:65], v[218:219], v[64:65]
	v_cvt_pk_bf16_f32 v67, v191, v207
	v_pk_add_f32 v[64:65], v[220:221], v[64:65]
	v_mfma_f32_32x32x16_bf16 v[0:15], v[124:127], v[116:119], v[0:15]
	v_add_f32_e64 v64, v222, v64
	v_add_f32_e64 v65, v223, v65
	v_cvt_pk_bf16_f32 v68, v201, v203
	v_add_f32_e64 v64, v168, v64
	v_add_f32_e64 v65, v169, v65
	v_cvt_pk_bf16_f32 v69, v205, v217
	v_pk_add_f32 v[64:65], v[156:157], v[64:65]
	v_cvt_pk_bf16_f32 v70, v219, v221
	v_pk_add_f32 v[64:65], v[158:159], v[64:65]
	v_cvt_pk_bf16_f32 v71, v223, v169
	v_pk_add_f32 v[64:65], v[166:167], v[64:65]
	v_cvt_pk_bf16_f32 v72, v157, v159
	v_pk_add_f32 v[64:65], v[176:177], v[64:65]
	v_cvt_pk_bf16_f32 v73, v167, v177
	v_pk_add_f32 v[64:65], v[178:179], v[64:65]
	v_cvt_pk_bf16_f32 v74, v179, v181
	v_pk_add_f32 v[64:65], v[180:181], v[64:65]
	v_cvt_pk_bf16_f32 v75, v183, v199
	v_pk_add_f32 v[64:65], v[182:183], v[64:65]
	v_cvt_pk_bf16_f32 v76, v197, v193
	v_pk_add_f32 v[64:65], v[198:199], v[64:65]
	v_cvt_pk_bf16_f32 v77, v195, v209
	v_pk_add_f32 v[64:65], v[196:197], v[64:65]
	v_cvt_pk_bf16_f32 v78, v211, v213
	v_pk_add_f32 v[64:65], v[192:193], v[64:65]
	v_cvt_pk_bf16_f32 v79, v215, v147
	v_pk_add_f32 v[64:65], v[194:195], v[64:65]
	s_nop 0
	v_pk_add_f32 v[64:65], v[208:209], v[64:65]
	s_nop 0
	v_pk_add_f32 v[64:65], v[210:211], v[64:65]
	s_nop 0
	v_pk_add_f32 v[64:65], v[212:213], v[64:65]
	s_nop 0
	v_pk_add_f32 v[64:65], v[214:215], v[64:65]
	s_nop 0
	v_pk_add_f32 v[64:65], v[146:147], v[64:65]
	s_nop 0
	v_pk_add_f32 v[112:113], v[64:65], v[64:65] op_sel:[0,1] op_sel_hi:[1,0]
	v_cvt_pk_bf16_f32 v64, v171, v173
	v_cvt_pk_bf16_f32 v65, v175, v185
	s_waitcnt vmcnt(0)
	s_barrier
; #define SBAR() __builtin_amdgcn_sched_barrier(0)
; __device__ __forceinline__ unsigned cvtpk(float lo, float hi) { return pg8::cvt_pk_bf16(lo, hi); }
; #define PV_RD2(D0, X) const s16x4 X##l0 = tr_read<v_rd_off2(D0, 0, 0)>(vb), X##h0 = tr_read<v_rd_off2(D0, 0, 1)>(vb), X##l1 = tr_read<v_rd_off2(D0, 1, 0)>(vb), X##h1 = tr_read<v_rd_off2(D0, 1, 1)>(vb), \
;                               X##l2 = tr_read<v_rd_off2(D0, 2, 0)>(vb), X##h2 = tr_read<v_rd_off2(D0, 2, 1)>(vb), X##l3 = tr_read<v_rd_off2(D0, 3, 0)>(vb), X##h3 = tr_read<v_rd_off2(D0, 3, 1)>(vb)
; __device__ __forceinline__ void pv_d02(f32x16* o, int vb, bf16x8 pa0, bf16x8 pa1, bf16x8 pa2, bf16x8 pa3) {
;   PV_RD2(0, a);
;   PV_RD2(1, b); asm volatile("s_waitcnt lgkmcnt(8)" ::: "memory"); SBAR(); PV_MM2(o[0], a); SBAR();
;   PV_RD2(2, c); asm volatile("s_waitcnt lgkmcnt(8)" ::: "memory"); SBAR(); PV_MM2(o[1], b); SBAR();
;   PV_RD2(3, d); asm volatile("s_waitcnt lgkmcnt(8)" ::: "memory"); SBAR(); PV_MM2(o[2], c); SBAR();
;   asm volatile("s_waitcnt lgkmcnt(0)" ::: "memory"); SBAR(); PV_MM2(o[3], d);
; }
; __device__ __forceinline__ void attn_dense_body(const bf16* Qb, const bf16* __restrict__ Kh, const bf16* __restrict__ Vh, const bf16* __restrict__ Zb, ...
;     ...
;   pv_d02(o, vb0 + sC * (int)SHM_V, pa0, pa1, pa2, pa3);
;     ...
;   { auto rr = __builtin_amdgcn_permlane32_swap(__float_as_uint(l_reg), __float_as_uint(l_reg), false, false); l_reg = __uint_as_float(rr[0]) + __uint_as_float(rr[1]); }
;   const float rl = __builtin_amdgcn_rcpf(l_reg);
;   { int lb = (wid * QBLK + r32) * LDO + 4 * hi; asm volatile("" : "+v"(lb));
;     unsigned short* Ow = (unsigned short*)Ob + lb; const unsigned short* Zw = (const unsigned short*)Zb + lb;
; #pragma unroll
;     for (int d0 = 0; d0 < 4; ++d0)
; #pragma unroll
;       for (int g = 0; g < 4; ++g) { const int co = d0 * 32 + 8 * g; const unsigned long long zz = *(const unsigned long long*)(Zw + co);
;         const float z0 = __uint_as_float((unsigned)(zz << 16)), z1 = __uint_as_float((unsigned)zz & 0xffff0000u), z2 = __uint_as_float((unsigned)(zz >> 32) << 16), z3 = __uint_as_float((unsigned)(zz >> 32) & 0xffff0000u);
;         const unsigned w0 = cvtpk(o[d0][4 * g + 0] * rl * z0, o[d0][4 * g + 1] * rl * z1), w1 = cvtpk(o[d0][4 * g + 2] * rl * z2, o[d0][4 * g + 3] * rl * z3);
	v_lshlrev_b32_e32 v222, 2, v245
	v_lshl_add_u32 v222, v160, 10, v222
	v_ashrrev_i32_e32 v223, 31, v222
	v_lshlrev_b64 v[222:223], 1, v[222:223]
	v_lshl_add_u64 v[220:221], s[40:41], 0, v[222:223]
	global_load_dwordx2 v[162:163], v[220:221], off
	global_load_dwordx2 v[164:165], v[220:221], off offset:16
	global_load_dwordx2 v[166:167], v[220:221], off offset:32
	global_load_dwordx2 v[168:169], v[220:221], off offset:48
	global_load_dwordx2 v[170:171], v[220:221], off offset:64
	global_load_dwordx2 v[172:173], v[220:221], off offset:80
	global_load_dwordx2 v[174:175], v[220:221], off offset:96
	global_load_dwordx2 v[176:177], v[220:221], off offset:112
	global_load_dwordx2 v[178:179], v[220:221], off offset:128
	global_load_dwordx2 v[180:181], v[220:221], off offset:144
	global_load_dwordx2 v[182:183], v[220:221], off offset:160
	global_load_dwordx2 v[184:185], v[220:221], off offset:176
	global_load_dwordx2 v[186:187], v[220:221], off offset:192
	global_load_dwordx2 v[188:189], v[220:221], off offset:208
	global_load_dwordx2 v[190:191], v[220:221], off offset:224
	global_load_dwordx2 v[192:193], v[220:221], off offset:240
	ds_read_b64_tr_b16 v[80:81], v246 offset:0
	ds_read_b64_tr_b16 v[82:83], v246 offset:0x100
	ds_read_b64_tr_b16 v[84:85], v246 offset:0x1000
	ds_read_b64_tr_b16 v[86:87], v246 offset:0x1100
	ds_read_b64_tr_b16 v[88:89], v246 offset:0x2000
	ds_read_b64_tr_b16 v[90:91], v246 offset:0x2100
	ds_read_b64_tr_b16 v[92:93], v246 offset:0x3000
	ds_read_b64_tr_b16 v[94:95], v246 offset:0x3100
	ds_read_b64_tr_b16 v[96:97], v246 offset:0x200
	ds_read_b64_tr_b16 v[98:99], v246 offset:0x300
	ds_read_b64_tr_b16 v[100:101], v246 offset:0x1200
	ds_read_b64_tr_b16 v[102:103], v246 offset:0x1300
	ds_read_b64_tr_b16 v[104:105], v246 offset:0x2200
	ds_read_b64_tr_b16 v[106:107], v246 offset:0x2300
	ds_read_b64_tr_b16 v[108:109], v246 offset:0x3200
	ds_read_b64_tr_b16 v[110:111], v246 offset:0x3300
	s_waitcnt lgkmcnt(8)
	s_nop 1
	v_mfma_f32_32x32x16_bf16 v[48:63], v[80:83], v[64:67], v[48:63]
	v_mfma_f32_32x32x16_bf16 v[48:63], v[84:87], v[68:71], v[48:63]
	v_mfma_f32_32x32x16_bf16 v[48:63], v[88:91], v[72:75], v[48:63]
	v_mfma_f32_32x32x16_bf16 v[48:63], v[92:95], v[76:79], v[48:63]
	ds_read_b64_tr_b16 v[80:81], v246 offset:0x400
	ds_read_b64_tr_b16 v[82:83], v246 offset:0x500
	ds_read_b64_tr_b16 v[84:85], v246 offset:0x1400
	ds_read_b64_tr_b16 v[86:87], v246 offset:0x1500
	ds_read_b64_tr_b16 v[88:89], v246 offset:0x2400
	ds_read_b64_tr_b16 v[90:91], v246 offset:0x2500
	ds_read_b64_tr_b16 v[92:93], v246 offset:0x3400
	ds_read_b64_tr_b16 v[94:95], v246 offset:0x3500
	s_waitcnt lgkmcnt(8)
	v_mfma_f32_32x32x16_bf16 v[32:47], v[96:99], v[64:67], v[32:47]
	v_mfma_f32_32x32x16_bf16 v[32:47], v[100:103], v[68:71], v[32:47]
	v_mfma_f32_32x32x16_bf16 v[32:47], v[104:107], v[72:75], v[32:47]
	v_mfma_f32_32x32x16_bf16 v[32:47], v[108:111], v[76:79], v[32:47]
	ds_read_b64_tr_b16 v[96:97], v246 offset:0x600
	ds_read_b64_tr_b16 v[98:99], v246 offset:0x700
	ds_read_b64_tr_b16 v[100:101], v246 offset:0x1600
	ds_read_b64_tr_b16 v[102:103], v246 offset:0x1700
	ds_read_b64_tr_b16 v[104:105], v246 offset:0x2600
	ds_read_b64_tr_b16 v[106:107], v246 offset:0x2700
	ds_read_b64_tr_b16 v[108:109], v246 offset:0x3600
	ds_read_b64_tr_b16 v[110:111], v246 offset:0x3700
	s_waitcnt lgkmcnt(8)
	v_mfma_f32_32x32x16_bf16 v[16:31], v[80:83], v[64:67], v[16:31]
	v_mfma_f32_32x32x16_bf16 v[16:31], v[84:87], v[68:71], v[16:31]
	v_mfma_f32_32x32x16_bf16 v[16:31], v[88:91], v[72:75], v[16:31]
	v_mfma_f32_32x32x16_bf16 v[16:31], v[92:95], v[76:79], v[16:31]
	s_waitcnt lgkmcnt(0)
	v_mfma_f32_32x32x16_bf16 v[0:15], v[96:99], v[64:67], v[0:15]
	v_mov_b32_e32 v64, v112
	s_nop 1
	v_permlane32_swap_b32_e32 v112, v64
	v_add_f32_e32 v64, v112, v64
	s_add_i32 s51, s51, s62
	s_cmp_ge_i32 s51, s6
	v_mfma_f32_32x32x16_bf16 v[0:15], v[100:103], v[68:71], v[0:15]
	v_rcp_f32_e32 v68, v64
	v_lshlrev_b32_e32 v64, 2, v245
	v_lshl_add_u32 v64, v160, 10, v64
	v_ashrrev_i32_e32 v65, 31, v64
	v_lshlrev_b64 v[66:67], 1, v[64:65]
	v_lshl_add_u64 v[64:65], s[24:25], 0, v[66:67]
	v_mfma_f32_32x32x16_bf16 v[0:15], v[104:107], v[72:75], v[0:15]
	v_mfma_f32_32x32x16_bf16 v[0:15], v[108:111], v[76:79], v[0:15]
	v_mul_f32_e32 v48, v48, v68
	v_mul_f32_e32 v49, v49, v68
	v_mul_f32_e32 v50, v50, v68
	v_mul_f32_e32 v51, v51, v68
	v_mul_f32_e32 v52, v52, v68
	v_mul_f32_e32 v53, v53, v68
	v_mul_f32_e32 v54, v54, v68
	v_mul_f32_e32 v55, v55, v68
	v_mul_f32_e32 v56, v56, v68
	v_mul_f32_e32 v57, v57, v68
	v_mul_f32_e32 v58, v58, v68
	v_mul_f32_e32 v59, v59, v68
	v_mul_f32_e32 v60, v60, v68
	v_mul_f32_e32 v61, v61, v68
	v_mul_f32_e32 v62, v62, v68
	v_mul_f32_e32 v63, v63, v68
	v_mul_f32_e32 v32, v32, v68
	v_mul_f32_e32 v33, v33, v68
	v_mul_f32_e32 v34, v34, v68
	v_mul_f32_e32 v35, v35, v68
	v_mul_f32_e32 v36, v36, v68
	v_mul_f32_e32 v37, v37, v68
	v_mul_f32_e32 v38, v38, v68
	v_mul_f32_e32 v39, v39, v68
	v_mul_f32_e32 v40, v40, v68
	v_mul_f32_e32 v41, v41, v68
	v_mul_f32_e32 v42, v42, v68
	v_mul_f32_e32 v43, v43, v68
	v_mul_f32_e32 v44, v44, v68
	v_mul_f32_e32 v45, v45, v68
	v_mul_f32_e32 v46, v46, v68
	v_mul_f32_e32 v47, v47, v68
	v_mul_f32_e32 v16, v16, v68
	v_mul_f32_e32 v17, v17, v68
	v_mul_f32_e32 v18, v18, v68
	v_mul_f32_e32 v19, v19, v68
	v_mul_f32_e32 v20, v20, v68
	v_mul_f32_e32 v21, v21, v68
	v_mul_f32_e32 v22, v22, v68
	v_mul_f32_e32 v23, v23, v68
	v_mul_f32_e32 v24, v24, v68
	v_mul_f32_e32 v25, v25, v68
	v_mul_f32_e32 v26, v26, v68
	v_mul_f32_e32 v27, v27, v68
	v_mul_f32_e32 v28, v28, v68
	v_mul_f32_e32 v29, v29, v68
	v_mul_f32_e32 v30, v30, v68
	v_mul_f32_e32 v31, v31, v68
	v_mul_f32_e32 v0, v0, v68
	v_mul_f32_e32 v1, v1, v68
	v_mul_f32_e32 v2, v2, v68
	v_mul_f32_e32 v3, v3, v68
	v_mul_f32_e32 v4, v4, v68
	v_mul_f32_e32 v5, v5, v68
	v_mul_f32_e32 v6, v6, v68
	v_mul_f32_e32 v7, v7, v68
	v_mul_f32_e32 v8, v8, v68
	v_mul_f32_e32 v9, v9, v68
	v_mul_f32_e32 v10, v10, v68
	v_mul_f32_e32 v11, v11, v68
	v_mul_f32_e32 v12, v12, v68
	v_mul_f32_e32 v13, v13, v68
	v_mul_f32_e32 v14, v14, v68
	v_mul_f32_e32 v15, v15, v68
	s_waitcnt vmcnt(0)
; __device__ __forceinline__ unsigned cvtpk(float lo, float hi) { return pg8::cvt_pk_bf16(lo, hi); }
; __device__ __forceinline__ void attn_dense_body(const bf16* Qb, const bf16* __restrict__ Kh, const bf16* __restrict__ Vh, const bf16* __restrict__ Zb, ...
;     ...
;   { int lb = (wid * QBLK + r32) * LDO + 4 * hi; asm volatile("" : "+v"(lb));
;     unsigned short* Ow = (unsigned short*)Ob + lb; const unsigned short* Zw = (const unsigned short*)Zb + lb;
; #pragma unroll
;     for (int d0 = 0; d0 < 4; ++d0)
; #pragma unroll
;       for (int g = 0; g < 4; ++g) { const int co = d0 * 32 + 8 * g; const unsigned long long zz = *(const unsigned long long*)(Zw + co);
;         const float z0 = __uint_as_float((unsigned)(zz << 16)), z1 = __uint_as_float((unsigned)zz & 0xffff0000u), z2 = __uint_as_float((unsigned)(zz >> 32) << 16), z3 = __uint_as_float((unsigned)(zz >> 32) & 0xffff0000u);
;         const unsigned w0 = cvtpk(o[d0][4 * g + 0] * rl * z0, o[d0][4 * g + 1] * rl * z1), w1 = cvtpk(o[d0][4 * g + 2] * rl * z2, o[d0][4 * g + 3] * rl * z3);
;         *(unsigned long long*)(Ow + co) = (unsigned long long)w0 | ((unsigned long long)w1 << 32); } }
	v_lshlrev_b32_e32 v194, 16, v162
	v_and_b32_e32 v195, 0xffff0000, v162
	v_lshlrev_b32_e32 v196, 16, v163
	v_and_b32_e32 v197, 0xffff0000, v163
	v_mul_f32_e32 v48, v48, v194
	v_mul_f32_e32 v49, v49, v195
	v_mul_f32_e32 v50, v50, v196
	v_mul_f32_e32 v51, v51, v197
	v_cvt_pk_bf16_f32 v48, v48, v49
	v_cvt_pk_bf16_f32 v49, v50, v51
	global_store_dwordx2 v[64:65], v[48:49], off
	v_lshlrev_b32_e32 v194, 16, v164
	v_and_b32_e32 v195, 0xffff0000, v164
	v_lshlrev_b32_e32 v196, 16, v165
	v_and_b32_e32 v197, 0xffff0000, v165
	v_mul_f32_e32 v52, v52, v194
	v_mul_f32_e32 v53, v53, v195
	v_mul_f32_e32 v54, v54, v196
	v_mul_f32_e32 v55, v55, v197
	v_cvt_pk_bf16_f32 v52, v52, v53
	v_cvt_pk_bf16_f32 v53, v54, v55
	global_store_dwordx2 v[64:65], v[52:53], off offset:16
	v_lshlrev_b32_e32 v194, 16, v166
	v_and_b32_e32 v195, 0xffff0000, v166
	v_lshlrev_b32_e32 v196, 16, v167
	v_and_b32_e32 v197, 0xffff0000, v167
	v_mul_f32_e32 v56, v56, v194
	v_mul_f32_e32 v57, v57, v195
	v_mul_f32_e32 v58, v58, v196
	v_mul_f32_e32 v59, v59, v197
	v_cvt_pk_bf16_f32 v56, v56, v57
	v_cvt_pk_bf16_f32 v57, v58, v59
	global_store_dwordx2 v[64:65], v[56:57], off offset:32
	v_lshlrev_b32_e32 v194, 16, v168
	v_and_b32_e32 v195, 0xffff0000, v168
	v_lshlrev_b32_e32 v196, 16, v169
	v_and_b32_e32 v197, 0xffff0000, v169
	v_mul_f32_e32 v60, v60, v194
	v_mul_f32_e32 v61, v61, v195
	v_mul_f32_e32 v62, v62, v196
	v_mul_f32_e32 v63, v63, v197
	v_cvt_pk_bf16_f32 v60, v60, v61
	v_cvt_pk_bf16_f32 v61, v62, v63
	global_store_dwordx2 v[64:65], v[60:61], off offset:48
	v_lshlrev_b32_e32 v194, 16, v170
	v_and_b32_e32 v195, 0xffff0000, v170
	v_lshlrev_b32_e32 v196, 16, v171
	v_and_b32_e32 v197, 0xffff0000, v171
	v_mul_f32_e32 v32, v32, v194
	v_mul_f32_e32 v33, v33, v195
	v_mul_f32_e32 v34, v34, v196
	v_mul_f32_e32 v35, v35, v197
	v_cvt_pk_bf16_f32 v32, v32, v33
	v_cvt_pk_bf16_f32 v33, v34, v35
	global_store_dwordx2 v[64:65], v[32:33], off offset:64
	v_lshlrev_b32_e32 v194, 16, v172
	v_and_b32_e32 v195, 0xffff0000, v172
	v_lshlrev_b32_e32 v196, 16, v173
	v_and_b32_e32 v197, 0xffff0000, v173
	v_mul_f32_e32 v36, v36, v194
	v_mul_f32_e32 v37, v37, v195
	v_mul_f32_e32 v38, v38, v196
	v_mul_f32_e32 v39, v39, v197
	v_cvt_pk_bf16_f32 v36, v36, v37
	v_cvt_pk_bf16_f32 v37, v38, v39
	global_store_dwordx2 v[64:65], v[36:37], off offset:80
	v_lshlrev_b32_e32 v194, 16, v174
	v_and_b32_e32 v195, 0xffff0000, v174
	v_lshlrev_b32_e32 v196, 16, v175
	v_and_b32_e32 v197, 0xffff0000, v175
	v_mul_f32_e32 v40, v40, v194
	v_mul_f32_e32 v41, v41, v195
	v_mul_f32_e32 v42, v42, v196
	v_mul_f32_e32 v43, v43, v197
	v_cvt_pk_bf16_f32 v40, v40, v41
	v_cvt_pk_bf16_f32 v41, v42, v43
	global_store_dwordx2 v[64:65], v[40:41], off offset:96
	v_lshlrev_b32_e32 v194, 16, v176
	v_and_b32_e32 v195, 0xffff0000, v176
	v_lshlrev_b32_e32 v196, 16, v177
	v_and_b32_e32 v197, 0xffff0000, v177
	v_mul_f32_e32 v44, v44, v194
	v_mul_f32_e32 v45, v45, v195
	v_mul_f32_e32 v46, v46, v196
	v_mul_f32_e32 v47, v47, v197
	v_cvt_pk_bf16_f32 v44, v44, v45
	v_cvt_pk_bf16_f32 v45, v46, v47
	global_store_dwordx2 v[64:65], v[44:45], off offset:112
	v_lshlrev_b32_e32 v194, 16, v178
	v_and_b32_e32 v195, 0xffff0000, v178
	v_lshlrev_b32_e32 v196, 16, v179
	v_and_b32_e32 v197, 0xffff0000, v179
	v_mul_f32_e32 v16, v16, v194
	v_mul_f32_e32 v17, v17, v195
	v_mul_f32_e32 v18, v18, v196
	v_mul_f32_e32 v19, v19, v197
	v_cvt_pk_bf16_f32 v16, v16, v17
	v_cvt_pk_bf16_f32 v17, v18, v19
	global_store_dwordx2 v[64:65], v[16:17], off offset:128
	v_lshlrev_b32_e32 v194, 16, v180
	v_and_b32_e32 v195, 0xffff0000, v180
	v_lshlrev_b32_e32 v196, 16, v181
	v_and_b32_e32 v197, 0xffff0000, v181
	v_mul_f32_e32 v20, v20, v194
	v_mul_f32_e32 v21, v21, v195
	v_mul_f32_e32 v22, v22, v196
	v_mul_f32_e32 v23, v23, v197
	v_cvt_pk_bf16_f32 v20, v20, v21
	v_cvt_pk_bf16_f32 v21, v22, v23
	global_store_dwordx2 v[64:65], v[20:21], off offset:144
	v_lshlrev_b32_e32 v194, 16, v182
	v_and_b32_e32 v195, 0xffff0000, v182
	v_lshlrev_b32_e32 v196, 16, v183
	v_and_b32_e32 v197, 0xffff0000, v183
	v_mul_f32_e32 v24, v24, v194
	v_mul_f32_e32 v25, v25, v195
	v_mul_f32_e32 v26, v26, v196
	v_mul_f32_e32 v27, v27, v197
	v_cvt_pk_bf16_f32 v24, v24, v25
	v_cvt_pk_bf16_f32 v25, v26, v27
	global_store_dwordx2 v[64:65], v[24:25], off offset:160
	v_lshlrev_b32_e32 v194, 16, v184
	v_and_b32_e32 v195, 0xffff0000, v184
	v_lshlrev_b32_e32 v196, 16, v185
	v_and_b32_e32 v197, 0xffff0000, v185
	v_mul_f32_e32 v28, v28, v194
	v_mul_f32_e32 v29, v29, v195
	v_mul_f32_e32 v30, v30, v196
	v_mul_f32_e32 v31, v31, v197
	v_cvt_pk_bf16_f32 v28, v28, v29
	v_cvt_pk_bf16_f32 v29, v30, v31
	global_store_dwordx2 v[64:65], v[28:29], off offset:176
	v_lshlrev_b32_e32 v194, 16, v186
	v_and_b32_e32 v195, 0xffff0000, v186
	v_lshlrev_b32_e32 v196, 16, v187
	v_and_b32_e32 v197, 0xffff0000, v187
	v_mul_f32_e32 v0, v0, v194
	v_mul_f32_e32 v1, v1, v195
	v_mul_f32_e32 v2, v2, v196
	v_mul_f32_e32 v3, v3, v197
	v_cvt_pk_bf16_f32 v0, v0, v1
	v_cvt_pk_bf16_f32 v1, v2, v3
	global_store_dwordx2 v[64:65], v[0:1], off offset:192
	v_lshlrev_b32_e32 v194, 16, v188
	v_and_b32_e32 v195, 0xffff0000, v188
	v_lshlrev_b32_e32 v196, 16, v189
	v_and_b32_e32 v197, 0xffff0000, v189
	v_mul_f32_e32 v4, v4, v194
	v_mul_f32_e32 v5, v5, v195
	v_mul_f32_e32 v6, v6, v196
	v_mul_f32_e32 v7, v7, v197
	v_cvt_pk_bf16_f32 v4, v4, v5
	v_cvt_pk_bf16_f32 v5, v6, v7
	global_store_dwordx2 v[64:65], v[4:5], off offset:208
	v_lshlrev_b32_e32 v194, 16, v190
	v_and_b32_e32 v195, 0xffff0000, v190
	v_lshlrev_b32_e32 v196, 16, v191
	v_and_b32_e32 v197, 0xffff0000, v191
	v_mul_f32_e32 v8, v8, v194
	v_mul_f32_e32 v9, v9, v195
	v_mul_f32_e32 v10, v10, v196
	v_mul_f32_e32 v11, v11, v197
	v_cvt_pk_bf16_f32 v8, v8, v9
	v_cvt_pk_bf16_f32 v9, v10, v11
	global_store_dwordx2 v[64:65], v[8:9], off offset:224
	v_lshlrev_b32_e32 v194, 16, v192
	v_and_b32_e32 v195, 0xffff0000, v192
	v_lshlrev_b32_e32 v196, 16, v193
	v_and_b32_e32 v197, 0xffff0000, v193
	v_mul_f32_e32 v12, v12, v194
	v_mul_f32_e32 v13, v13, v195
	v_mul_f32_e32 v14, v14, v196
	v_mul_f32_e32 v15, v15, v197
	v_cvt_pk_bf16_f32 v12, v12, v13
	v_cvt_pk_bf16_f32 v13, v14, v15
	global_store_dwordx2 v[64:65], v[12:13], off offset:240
	s_cbranch_scc0 .LBB0_112
	v_readlane_b32 s84, v255, 16
	v_readlane_b32 s85, v255, 17
	v_readlane_b32 s86, v255, 18
	v_readlane_b32 s87, v255, 19
	s_nop 3
